# seams 1-5: single counted arrive (atomic with return); the last workgroup releases one 4KiB-spaced flag line per workgroup, each workgroup polls only its own line (no shared poll address)
# speedup vs baseline: 1.0182x; 1.0182x over previous
; __device__ __forceinline__ unsigned cvt_pk_bf16(float lo, float hi) { unsigned r; asm volatile("v_cvt_pk_bf16_f32 %0, %1, %2" : "=v"(r) : "v"(lo), "v"(hi)); return r; }
; __global__ void __launch_bounds__(512, 2) hybrid_fwd(Args a) {
;     ...
;     if (bx == 0 && tid < 72) __hip_atomic_store((unsigned*)(ws + WS_CTL) + 1024 * (tid / 9) + 64 * (tid % 9), 0u, __ATOMIC_RELAXED, __HIP_MEMORY_SCOPE_AGENT);
;     {
;         const size_t gt = (size_t)bx * 512 + tid, GT = (size_t)G * 512;
;         {
;             const size_t NCH = (size_t)M * D / 8;
;             for (size_t i0 = gt; i0 < NCH; i0 += 4 * GT) {
;                 f32x4 v[4][2];
; #pragma unroll
;                 for (int u = 0; u < 4; ++u) { const size_t i = i0 + (size_t)u * GT; if (i < NCH) { v[u][0] = ((const f32x4*)a.x)[2 * i]; v[u][1] = ((const f32x4*)a.x)[2 * i + 1]; } }
; #pragma unroll
;                 for (int u = 0; u < 4; ++u) { const size_t i = i0 + (size_t)u * GT; if (i < NCH) {
;                     u32x4 w; w.x = cvt_pk_bf16(v[u][0][0], v[u][0][1]); w.y = cvt_pk_bf16(v[u][0][2], v[u][0][3]); w.z = cvt_pk_bf16(v[u][1][0], v[u][1][1]); w.w = cvt_pk_bf16(v[u][1][2], v[u][1][3]);
;                     if (a.n_bf16 > 0) ((u32x4*)XB)[i] = w;
;                     const unsigned p0 = pack_fp8x4(v[u][0][0], v[u][0][1], v[u][0][2], v[u][0][3]), p1 = pack_fp8x4(v[u][1][0], v[u][1][1], v[u][1][2], v[u][1][3]);
;                     ((u32x2*)XB8)[i] = (u32x2){p0, p1}; } }
.LBB0_2:
	s_or_b64 exec, exec, s[4:5]
	v_cmp_eq_u32_e32 vcc, 0, v160
	s_and_saveexec_b64 s[4:5], vcc
	s_lshl_b32 s100, s2, 12
	s_add_u32 s100, s100, 0x8e10000
	v_mov_b32_e32 v243, s100
	v_mov_b32_e32 v244, 0
	s_waitcnt lgkmcnt(0)
	global_store_dword v243, v244, s[90:91] sc1
	s_or_b64 exec, exec, s[4:5]
	s_ashr_i32 s3, s2, 31
	s_lshl_b64 s[4:5], s[2:3], 9
	v_mov_b32_e32 v161, 0
	v_lshl_add_u64 v[38:39], s[4:5], 0, v[160:161]
	s_waitcnt lgkmcnt(0)
	s_ashr_i32 s93, s92, 31
	s_mov_b64 s[12:13], 0x400000
	s_lshl_b64 s[14:15], s[92:93], 9
	v_cmp_gt_u64_e32 vcc, s[12:13], v[38:39]
	v_lshlrev_b32_e32 v40, 3, v160
	s_mov_b32 s100, 0
	s_cmp_lg_u32 s92, 0x100
	s_cbranch_scc1 .Lp0_done
	s_load_dword s16, s[70:71], 0x1c0
	s_load_dwordx2 s[18:19], s[70:71], 0x1c8
	s_load_dwordx2 s[6:7], s[70:71], 0x0
	s_load_dwordx2 s[20:21], s[70:71], 0x8
	s_load_dwordx2 s[22:23], s[70:71], 0x10
	s_waitcnt lgkmcnt(0)
	s_cmp_lg_u32 s16, 0
	s_cbranch_scc1 .Lp0_done
	s_cmp_lg_u32 s18, -1
	s_cbranch_scc1 .Lp0_done
	s_cmpk_lg_u32 s19, 0x1fff
	s_cbranch_scc1 .Lp0_done
	v_lshl_add_u32 v1, s2, 9, v160
	v_and_b32_e32 v4, 63, v160
	v_lshlrev_b32_e32 v2, 5, v1
	v_lshlrev_b32_e32 v3, 3, v1
	s_mov_b64 s[8:9], s[88:89]
	global_load_dwordx4 v[64:67], v2, s[6:7] nt
	global_load_dwordx4 v[68:71], v2, s[6:7] offset:16 nt
	s_add_u32 s6, s6, 0x400000
	s_addc_u32 s7, s7, 0
	global_load_dwordx4 v[72:75], v2, s[6:7] nt
	global_load_dwordx4 v[76:79], v2, s[6:7] offset:16 nt
	s_add_u32 s6, s6, 0x400000
	s_addc_u32 s7, s7, 0
	global_load_dwordx4 v[80:83], v2, s[6:7] nt
	global_load_dwordx4 v[84:87], v2, s[6:7] offset:16 nt
	s_add_u32 s6, s6, 0x400000
	s_addc_u32 s7, s7, 0
	global_load_dwordx4 v[88:91], v2, s[6:7] nt
	global_load_dwordx4 v[92:95], v2, s[6:7] offset:16 nt
	s_add_u32 s6, s6, 0x400000
	s_addc_u32 s7, s7, 0
	global_load_dwordx4 v[96:99], v2, s[6:7] nt
	global_load_dwordx4 v[100:103], v2, s[6:7] offset:16 nt
	s_add_u32 s6, s6, 0x400000
	s_addc_u32 s7, s7, 0
	global_load_dwordx4 v[104:107], v2, s[6:7] nt
	global_load_dwordx4 v[108:111], v2, s[6:7] offset:16 nt
	s_add_u32 s6, s6, 0x400000
	s_addc_u32 s7, s7, 0
	global_load_dwordx4 v[112:115], v2, s[6:7] nt
	global_load_dwordx4 v[116:119], v2, s[6:7] offset:16 nt
	s_add_u32 s6, s6, 0x400000
	s_addc_u32 s7, s7, 0
	global_load_dwordx4 v[120:123], v2, s[6:7] nt
	global_load_dwordx4 v[124:127], v2, s[6:7] offset:16 nt
	s_add_u32 s6, s6, 0x400000
	s_addc_u32 s7, s7, 0
	s_waitcnt vmcnt(14)
	v_cvt_pk_fp8_f32 v8, v64, v65
	v_cvt_pk_fp8_f32 v9, v66, v67
	v_cvt_pk_fp8_f32 v10, v68, v69
	v_cvt_pk_fp8_f32 v11, v70, v71
	v_and_b32_e32 v8, 0xffff, v8
	v_and_b32_e32 v10, 0xffff, v10
	v_lshl_or_b32 v128, v9, 16, v8
	v_lshl_or_b32 v129, v11, 16, v10
	global_store_dwordx2 v3, v[128:129], s[8:9]
	s_add_u32 s8, s8, 0x100000
	s_addc_u32 s9, s9, 0
	global_load_dwordx4 v[64:67], v2, s[6:7] nt
	global_load_dwordx4 v[68:71], v2, s[6:7] offset:16 nt
	s_add_u32 s6, s6, 0x400000
	s_addc_u32 s7, s7, 0
	s_waitcnt vmcnt(15)
	v_cvt_pk_fp8_f32 v8, v72, v73
	v_cvt_pk_fp8_f32 v9, v74, v75
	v_cvt_pk_fp8_f32 v10, v76, v77
	v_cvt_pk_fp8_f32 v11, v78, v79
	v_and_b32_e32 v8, 0xffff, v8
	v_and_b32_e32 v10, 0xffff, v10
	v_lshl_or_b32 v130, v9, 16, v8
	v_lshl_or_b32 v131, v11, 16, v10
	global_store_dwordx2 v3, v[130:131], s[8:9]
	s_add_u32 s8, s8, 0x100000
	s_addc_u32 s9, s9, 0
	global_load_dwordx4 v[72:75], v2, s[6:7] nt
	global_load_dwordx4 v[76:79], v2, s[6:7] offset:16 nt
	s_add_u32 s6, s6, 0x400000
	s_addc_u32 s7, s7, 0
	s_waitcnt vmcnt(16)
	v_cvt_pk_fp8_f32 v8, v80, v81
	v_cvt_pk_fp8_f32 v9, v82, v83
	v_cvt_pk_fp8_f32 v10, v84, v85
	v_cvt_pk_fp8_f32 v11, v86, v87
	v_and_b32_e32 v8, 0xffff, v8
	v_and_b32_e32 v10, 0xffff, v10
	v_lshl_or_b32 v132, v9, 16, v8
	v_lshl_or_b32 v133, v11, 16, v10
	global_store_dwordx2 v3, v[132:133], s[8:9]
	s_add_u32 s8, s8, 0x100000
	s_addc_u32 s9, s9, 0
	global_load_dwordx4 v[80:83], v2, s[6:7] nt
	global_load_dwordx4 v[84:87], v2, s[6:7] offset:16 nt
	s_add_u32 s6, s6, 0x400000
	s_addc_u32 s7, s7, 0
	s_waitcnt vmcnt(17)
	v_cvt_pk_fp8_f32 v8, v88, v89
	v_cvt_pk_fp8_f32 v9, v90, v91
	v_cvt_pk_fp8_f32 v10, v92, v93
	v_cvt_pk_fp8_f32 v11, v94, v95
	v_and_b32_e32 v8, 0xffff, v8
	v_and_b32_e32 v10, 0xffff, v10
	v_lshl_or_b32 v134, v9, 16, v8
	v_lshl_or_b32 v135, v11, 16, v10
	global_store_dwordx2 v3, v[134:135], s[8:9]
	s_add_u32 s8, s8, 0x100000
	s_addc_u32 s9, s9, 0
	global_load_dwordx4 v[88:91], v2, s[6:7] nt
	global_load_dwordx4 v[92:95], v2, s[6:7] offset:16 nt
	s_add_u32 s6, s6, 0x400000
	s_addc_u32 s7, s7, 0
	s_waitcnt vmcnt(18)
	v_cvt_pk_fp8_f32 v8, v96, v97
	v_cvt_pk_fp8_f32 v9, v98, v99
	v_cvt_pk_fp8_f32 v10, v100, v101
	v_cvt_pk_fp8_f32 v11, v102, v103
	v_and_b32_e32 v8, 0xffff, v8
	v_and_b32_e32 v10, 0xffff, v10
	v_lshl_or_b32 v136, v9, 16, v8
	v_lshl_or_b32 v137, v11, 16, v10
	global_store_dwordx2 v3, v[136:137], s[8:9]
	s_add_u32 s8, s8, 0x100000
	s_addc_u32 s9, s9, 0
	global_load_dwordx4 v[96:99], v2, s[6:7] nt
	global_load_dwordx4 v[100:103], v2, s[6:7] offset:16 nt
	s_add_u32 s6, s6, 0x400000
	s_addc_u32 s7, s7, 0
	s_waitcnt vmcnt(19)
	v_cvt_pk_fp8_f32 v8, v104, v105
	v_cvt_pk_fp8_f32 v9, v106, v107
	v_cvt_pk_fp8_f32 v10, v108, v109
	v_cvt_pk_fp8_f32 v11, v110, v111
	v_and_b32_e32 v8, 0xffff, v8
	v_and_b32_e32 v10, 0xffff, v10
	v_lshl_or_b32 v138, v9, 16, v8
	v_lshl_or_b32 v139, v11, 16, v10
	global_store_dwordx2 v3, v[138:139], s[8:9]
	s_add_u32 s8, s8, 0x100000
	s_addc_u32 s9, s9, 0
	global_load_dwordx4 v[104:107], v2, s[6:7] nt
	global_load_dwordx4 v[108:111], v2, s[6:7] offset:16 nt
	s_add_u32 s6, s6, 0x400000
	s_addc_u32 s7, s7, 0
	s_waitcnt vmcnt(20)
; __device__ __forceinline__ unsigned cvt_pk_bf16(float lo, float hi) { unsigned r; asm volatile("v_cvt_pk_bf16_f32 %0, %1, %2" : "=v"(r) : "v"(lo), "v"(hi)); return r; }
; __global__ void __launch_bounds__(512, 2) hybrid_fwd(Args a) {
;     ...
;             for (size_t i0 = gt; i0 < NCH; i0 += 4 * GT) {
;                 f32x4 v[4][2];
; #pragma unroll
;                 for (int u = 0; u < 4; ++u) { const size_t i = i0 + (size_t)u * GT; if (i < NCH) { v[u][0] = ((const f32x4*)a.x)[2 * i]; v[u][1] = ((const f32x4*)a.x)[2 * i + 1]; } }
; #pragma unroll
;                 for (int u = 0; u < 4; ++u) { const size_t i = i0 + (size_t)u * GT; if (i < NCH) {
;                     u32x4 w; w.x = cvt_pk_bf16(v[u][0][0], v[u][0][1]); w.y = cvt_pk_bf16(v[u][0][2], v[u][0][3]); w.z = cvt_pk_bf16(v[u][1][0], v[u][1][1]); w.w = cvt_pk_bf16(v[u][1][2], v[u][1][3]);
;                     if (a.n_bf16 > 0) ((u32x4*)XB)[i] = w;
;                     const unsigned p0 = pack_fp8x4(v[u][0][0], v[u][0][1], v[u][0][2], v[u][0][3]), p1 = pack_fp8x4(v[u][1][0], v[u][1][1], v[u][1][2], v[u][1][3]);
;                     ((u32x2*)XB8)[i] = (u32x2){p0, p1}; } }
	v_cvt_pk_fp8_f32 v8, v112, v113
	v_cvt_pk_fp8_f32 v9, v114, v115
	v_cvt_pk_fp8_f32 v10, v116, v117
	v_cvt_pk_fp8_f32 v11, v118, v119
	v_and_b32_e32 v8, 0xffff, v8
	v_and_b32_e32 v10, 0xffff, v10
	v_lshl_or_b32 v140, v9, 16, v8
	v_lshl_or_b32 v141, v11, 16, v10
	global_store_dwordx2 v3, v[140:141], s[8:9]
	s_add_u32 s8, s8, 0x100000
	s_addc_u32 s9, s9, 0
	global_load_dwordx4 v[112:115], v2, s[6:7] nt
	global_load_dwordx4 v[116:119], v2, s[6:7] offset:16 nt
	s_add_u32 s6, s6, 0x400000
	s_addc_u32 s7, s7, 0
	s_waitcnt vmcnt(21)
	v_cvt_pk_fp8_f32 v8, v120, v121
	v_cvt_pk_fp8_f32 v9, v122, v123
	v_cvt_pk_fp8_f32 v10, v124, v125
	v_cvt_pk_fp8_f32 v11, v126, v127
	v_and_b32_e32 v8, 0xffff, v8
	v_and_b32_e32 v10, 0xffff, v10
	v_lshl_or_b32 v142, v9, 16, v8
	v_lshl_or_b32 v143, v11, 16, v10
	global_store_dwordx2 v3, v[142:143], s[8:9]
	s_add_u32 s8, s8, 0x100000
	s_addc_u32 s9, s9, 0
	global_load_dwordx4 v[120:123], v2, s[6:7] nt
	global_load_dwordx4 v[124:127], v2, s[6:7] offset:16 nt
	s_add_u32 s6, s6, 0x400000
	s_addc_u32 s7, s7, 0
	s_waitcnt vmcnt(21)
	v_cvt_pk_fp8_f32 v8, v64, v65
	v_cvt_pk_fp8_f32 v9, v66, v67
	v_cvt_pk_fp8_f32 v10, v68, v69
	v_cvt_pk_fp8_f32 v11, v70, v71
	v_and_b32_e32 v8, 0xffff, v8
	v_and_b32_e32 v10, 0xffff, v10
	v_lshl_or_b32 v128, v9, 16, v8
	v_lshl_or_b32 v129, v11, 16, v10
	global_store_dwordx2 v3, v[128:129], s[8:9]
	s_add_u32 s8, s8, 0x100000
	s_addc_u32 s9, s9, 0
	global_load_dwordx4 v[64:67], v2, s[6:7] nt
	global_load_dwordx4 v[68:71], v2, s[6:7] offset:16 nt
	s_add_u32 s6, s6, 0x400000
	s_addc_u32 s7, s7, 0
	s_waitcnt vmcnt(21)
	v_cvt_pk_fp8_f32 v8, v72, v73
	v_cvt_pk_fp8_f32 v9, v74, v75
	v_cvt_pk_fp8_f32 v10, v76, v77
	v_cvt_pk_fp8_f32 v11, v78, v79
	v_and_b32_e32 v8, 0xffff, v8
	v_and_b32_e32 v10, 0xffff, v10
	v_lshl_or_b32 v130, v9, 16, v8
	v_lshl_or_b32 v131, v11, 16, v10
	global_store_dwordx2 v3, v[130:131], s[8:9]
	s_add_u32 s8, s8, 0x100000
	s_addc_u32 s9, s9, 0
	global_load_dwordx4 v[72:75], v2, s[6:7] nt
	global_load_dwordx4 v[76:79], v2, s[6:7] offset:16 nt
	s_add_u32 s6, s6, 0x400000
	s_addc_u32 s7, s7, 0
	s_waitcnt vmcnt(21)
	v_cvt_pk_fp8_f32 v8, v80, v81
	v_cvt_pk_fp8_f32 v9, v82, v83
	v_cvt_pk_fp8_f32 v10, v84, v85
	v_cvt_pk_fp8_f32 v11, v86, v87
	v_and_b32_e32 v8, 0xffff, v8
	v_and_b32_e32 v10, 0xffff, v10
	v_lshl_or_b32 v132, v9, 16, v8
	v_lshl_or_b32 v133, v11, 16, v10
	global_store_dwordx2 v3, v[132:133], s[8:9]
	s_add_u32 s8, s8, 0x100000
	s_addc_u32 s9, s9, 0
	global_load_dwordx4 v[80:83], v2, s[6:7] nt
	global_load_dwordx4 v[84:87], v2, s[6:7] offset:16 nt
	s_add_u32 s6, s6, 0x400000
	s_addc_u32 s7, s7, 0
	s_waitcnt vmcnt(21)
	v_cvt_pk_fp8_f32 v8, v88, v89
	v_cvt_pk_fp8_f32 v9, v90, v91
	v_cvt_pk_fp8_f32 v10, v92, v93
	v_cvt_pk_fp8_f32 v11, v94, v95
	v_and_b32_e32 v8, 0xffff, v8
	v_and_b32_e32 v10, 0xffff, v10
	v_lshl_or_b32 v134, v9, 16, v8
	v_lshl_or_b32 v135, v11, 16, v10
	global_store_dwordx2 v3, v[134:135], s[8:9]
	s_add_u32 s8, s8, 0x100000
	s_addc_u32 s9, s9, 0
	global_load_dwordx4 v[88:91], v2, s[6:7] nt
	global_load_dwordx4 v[92:95], v2, s[6:7] offset:16 nt
	s_add_u32 s6, s6, 0x400000
	s_addc_u32 s7, s7, 0
	s_waitcnt vmcnt(21)
	v_cvt_pk_fp8_f32 v8, v96, v97
	v_cvt_pk_fp8_f32 v9, v98, v99
	v_cvt_pk_fp8_f32 v10, v100, v101
	v_cvt_pk_fp8_f32 v11, v102, v103
	v_and_b32_e32 v8, 0xffff, v8
	v_and_b32_e32 v10, 0xffff, v10
	v_lshl_or_b32 v136, v9, 16, v8
	v_lshl_or_b32 v137, v11, 16, v10
	global_store_dwordx2 v3, v[136:137], s[8:9]
	s_add_u32 s8, s8, 0x100000
	s_addc_u32 s9, s9, 0
	global_load_dwordx4 v[96:99], v2, s[6:7] nt
	global_load_dwordx4 v[100:103], v2, s[6:7] offset:16 nt
	s_add_u32 s6, s6, 0x400000
	s_addc_u32 s7, s7, 0
	s_waitcnt vmcnt(21)
	v_cvt_pk_fp8_f32 v8, v104, v105
	v_cvt_pk_fp8_f32 v9, v106, v107
	v_cvt_pk_fp8_f32 v10, v108, v109
	v_cvt_pk_fp8_f32 v11, v110, v111
	v_and_b32_e32 v8, 0xffff, v8
	v_and_b32_e32 v10, 0xffff, v10
	v_lshl_or_b32 v138, v9, 16, v8
	v_lshl_or_b32 v139, v11, 16, v10
	global_store_dwordx2 v3, v[138:139], s[8:9]
	s_add_u32 s8, s8, 0x100000
	s_addc_u32 s9, s9, 0
	global_load_dwordx4 v[104:107], v2, s[6:7] nt
	global_load_dwordx4 v[108:111], v2, s[6:7] offset:16 nt
	s_add_u32 s6, s6, 0x400000
	s_addc_u32 s7, s7, 0
	s_waitcnt vmcnt(21)
	v_cvt_pk_fp8_f32 v8, v112, v113
	v_cvt_pk_fp8_f32 v9, v114, v115
	v_cvt_pk_fp8_f32 v10, v116, v117
	v_cvt_pk_fp8_f32 v11, v118, v119
	v_and_b32_e32 v8, 0xffff, v8
	v_and_b32_e32 v10, 0xffff, v10
	v_lshl_or_b32 v140, v9, 16, v8
	v_lshl_or_b32 v141, v11, 16, v10
	global_store_dwordx2 v3, v[140:141], s[8:9]
	s_add_u32 s8, s8, 0x100000
	s_addc_u32 s9, s9, 0
	global_load_dwordx4 v[112:115], v2, s[6:7] nt
	global_load_dwordx4 v[116:119], v2, s[6:7] offset:16 nt
	s_add_u32 s6, s6, 0x400000
	s_addc_u32 s7, s7, 0
	s_waitcnt vmcnt(21)
	v_cvt_pk_fp8_f32 v8, v120, v121
	v_cvt_pk_fp8_f32 v9, v122, v123
	v_cvt_pk_fp8_f32 v10, v124, v125
	v_cvt_pk_fp8_f32 v11, v126, v127
	v_and_b32_e32 v8, 0xffff, v8
	v_and_b32_e32 v10, 0xffff, v10
	v_lshl_or_b32 v142, v9, 16, v8
	v_lshl_or_b32 v143, v11, 16, v10
	global_store_dwordx2 v3, v[142:143], s[8:9]
	s_add_u32 s8, s8, 0x100000
	s_addc_u32 s9, s9, 0
	global_load_dwordx4 v[120:123], v2, s[6:7] nt
	global_load_dwordx4 v[124:127], v2, s[6:7] offset:16 nt
	s_add_u32 s6, s6, 0x400000
	s_addc_u32 s7, s7, 0
	s_waitcnt vmcnt(21)
	v_cvt_pk_fp8_f32 v8, v64, v65
	v_cvt_pk_fp8_f32 v9, v66, v67
	v_cvt_pk_fp8_f32 v10, v68, v69
	v_cvt_pk_fp8_f32 v11, v70, v71
	v_and_b32_e32 v8, 0xffff, v8
	v_and_b32_e32 v10, 0xffff, v10
	v_lshl_or_b32 v128, v9, 16, v8
	v_lshl_or_b32 v129, v11, 16, v10
	global_store_dwordx2 v3, v[128:129], s[8:9]
	s_add_u32 s8, s8, 0x100000
	s_addc_u32 s9, s9, 0
	global_load_dwordx4 v[64:67], v2, s[6:7] nt
	global_load_dwordx4 v[68:71], v2, s[6:7] offset:16 nt
	s_add_u32 s6, s6, 0x400000
	s_addc_u32 s7, s7, 0
	s_waitcnt vmcnt(21)
; __device__ __forceinline__ unsigned cvt_pk_bf16(float lo, float hi) { unsigned r; asm volatile("v_cvt_pk_bf16_f32 %0, %1, %2" : "=v"(r) : "v"(lo), "v"(hi)); return r; }
; __global__ void __launch_bounds__(512, 2) hybrid_fwd(Args a) {
;     ...
;             for (size_t i0 = gt; i0 < NCH; i0 += 4 * GT) {
;                 f32x4 v[4][2];
; #pragma unroll
;                 for (int u = 0; u < 4; ++u) { const size_t i = i0 + (size_t)u * GT; if (i < NCH) { v[u][0] = ((const f32x4*)a.x)[2 * i]; v[u][1] = ((const f32x4*)a.x)[2 * i + 1]; } }
; #pragma unroll
;                 for (int u = 0; u < 4; ++u) { const size_t i = i0 + (size_t)u * GT; if (i < NCH) {
;                     u32x4 w; w.x = cvt_pk_bf16(v[u][0][0], v[u][0][1]); w.y = cvt_pk_bf16(v[u][0][2], v[u][0][3]); w.z = cvt_pk_bf16(v[u][1][0], v[u][1][1]); w.w = cvt_pk_bf16(v[u][1][2], v[u][1][3]);
;                     if (a.n_bf16 > 0) ((u32x4*)XB)[i] = w;
;                     const unsigned p0 = pack_fp8x4(v[u][0][0], v[u][0][1], v[u][0][2], v[u][0][3]), p1 = pack_fp8x4(v[u][1][0], v[u][1][1], v[u][1][2], v[u][1][3]);
;                     ((u32x2*)XB8)[i] = (u32x2){p0, p1}; } }
	v_cvt_pk_fp8_f32 v8, v72, v73
	v_cvt_pk_fp8_f32 v9, v74, v75
	v_cvt_pk_fp8_f32 v10, v76, v77
	v_cvt_pk_fp8_f32 v11, v78, v79
	v_and_b32_e32 v8, 0xffff, v8
	v_and_b32_e32 v10, 0xffff, v10
	v_lshl_or_b32 v130, v9, 16, v8
	v_lshl_or_b32 v131, v11, 16, v10
	global_store_dwordx2 v3, v[130:131], s[8:9]
	s_add_u32 s8, s8, 0x100000
	s_addc_u32 s9, s9, 0
	global_load_dwordx4 v[72:75], v2, s[6:7] nt
	global_load_dwordx4 v[76:79], v2, s[6:7] offset:16 nt
	s_add_u32 s6, s6, 0x400000
	s_addc_u32 s7, s7, 0
	s_waitcnt vmcnt(21)
	v_cvt_pk_fp8_f32 v8, v80, v81
	v_cvt_pk_fp8_f32 v9, v82, v83
	v_cvt_pk_fp8_f32 v10, v84, v85
	v_cvt_pk_fp8_f32 v11, v86, v87
	v_and_b32_e32 v8, 0xffff, v8
	v_and_b32_e32 v10, 0xffff, v10
	v_lshl_or_b32 v132, v9, 16, v8
	v_lshl_or_b32 v133, v11, 16, v10
	global_store_dwordx2 v3, v[132:133], s[8:9]
	s_add_u32 s8, s8, 0x100000
	s_addc_u32 s9, s9, 0
	global_load_dwordx4 v[80:83], v2, s[6:7] nt
	global_load_dwordx4 v[84:87], v2, s[6:7] offset:16 nt
	s_add_u32 s6, s6, 0x400000
	s_addc_u32 s7, s7, 0
	s_waitcnt vmcnt(21)
	v_cvt_pk_fp8_f32 v8, v88, v89
	v_cvt_pk_fp8_f32 v9, v90, v91
	v_cvt_pk_fp8_f32 v10, v92, v93
	v_cvt_pk_fp8_f32 v11, v94, v95
	v_and_b32_e32 v8, 0xffff, v8
	v_and_b32_e32 v10, 0xffff, v10
	v_lshl_or_b32 v134, v9, 16, v8
	v_lshl_or_b32 v135, v11, 16, v10
	global_store_dwordx2 v3, v[134:135], s[8:9]
	s_add_u32 s8, s8, 0x100000
	s_addc_u32 s9, s9, 0
	global_load_dwordx4 v[88:91], v2, s[6:7] nt
	global_load_dwordx4 v[92:95], v2, s[6:7] offset:16 nt
	s_add_u32 s6, s6, 0x400000
	s_addc_u32 s7, s7, 0
	s_waitcnt vmcnt(21)
	v_cvt_pk_fp8_f32 v8, v96, v97
	v_cvt_pk_fp8_f32 v9, v98, v99
	v_cvt_pk_fp8_f32 v10, v100, v101
	v_cvt_pk_fp8_f32 v11, v102, v103
	v_and_b32_e32 v8, 0xffff, v8
	v_and_b32_e32 v10, 0xffff, v10
	v_lshl_or_b32 v136, v9, 16, v8
	v_lshl_or_b32 v137, v11, 16, v10
	global_store_dwordx2 v3, v[136:137], s[8:9]
	s_add_u32 s8, s8, 0x100000
	s_addc_u32 s9, s9, 0
	global_load_dwordx4 v[96:99], v2, s[6:7] nt
	global_load_dwordx4 v[100:103], v2, s[6:7] offset:16 nt
	s_add_u32 s6, s6, 0x400000
	s_addc_u32 s7, s7, 0
	s_waitcnt vmcnt(21)
	v_cvt_pk_fp8_f32 v8, v104, v105
	v_cvt_pk_fp8_f32 v9, v106, v107
	v_cvt_pk_fp8_f32 v10, v108, v109
	v_cvt_pk_fp8_f32 v11, v110, v111
	v_and_b32_e32 v8, 0xffff, v8
	v_and_b32_e32 v10, 0xffff, v10
	v_lshl_or_b32 v138, v9, 16, v8
	v_lshl_or_b32 v139, v11, 16, v10
	global_store_dwordx2 v3, v[138:139], s[8:9]
	s_add_u32 s8, s8, 0x100000
	s_addc_u32 s9, s9, 0
	global_load_dwordx4 v[104:107], v2, s[6:7] nt
	global_load_dwordx4 v[108:111], v2, s[6:7] offset:16 nt
	s_add_u32 s6, s6, 0x400000
	s_addc_u32 s7, s7, 0
	s_waitcnt vmcnt(21)
	v_cvt_pk_fp8_f32 v8, v112, v113
	v_cvt_pk_fp8_f32 v9, v114, v115
	v_cvt_pk_fp8_f32 v10, v116, v117
	v_cvt_pk_fp8_f32 v11, v118, v119
	v_and_b32_e32 v8, 0xffff, v8
	v_and_b32_e32 v10, 0xffff, v10
	v_lshl_or_b32 v140, v9, 16, v8
	v_lshl_or_b32 v141, v11, 16, v10
	global_store_dwordx2 v3, v[140:141], s[8:9]
	s_add_u32 s8, s8, 0x100000
	s_addc_u32 s9, s9, 0
	global_load_dwordx4 v[112:115], v2, s[6:7] nt
	global_load_dwordx4 v[116:119], v2, s[6:7] offset:16 nt
	s_add_u32 s6, s6, 0x400000
	s_addc_u32 s7, s7, 0
	s_waitcnt vmcnt(21)
	v_cvt_pk_fp8_f32 v8, v120, v121
	v_cvt_pk_fp8_f32 v9, v122, v123
	v_cvt_pk_fp8_f32 v10, v124, v125
	v_cvt_pk_fp8_f32 v11, v126, v127
	v_and_b32_e32 v8, 0xffff, v8
	v_and_b32_e32 v10, 0xffff, v10
	v_lshl_or_b32 v142, v9, 16, v8
	v_lshl_or_b32 v143, v11, 16, v10
	global_store_dwordx2 v3, v[142:143], s[8:9]
	s_add_u32 s8, s8, 0x100000
	s_addc_u32 s9, s9, 0
	global_load_dwordx4 v[120:123], v2, s[6:7] nt
	global_load_dwordx4 v[124:127], v2, s[6:7] offset:16 nt
	s_add_u32 s6, s6, 0x400000
	s_addc_u32 s7, s7, 0
	s_waitcnt vmcnt(21)
	v_cvt_pk_fp8_f32 v8, v64, v65
	v_cvt_pk_fp8_f32 v9, v66, v67
	v_cvt_pk_fp8_f32 v10, v68, v69
	v_cvt_pk_fp8_f32 v11, v70, v71
	v_and_b32_e32 v8, 0xffff, v8
	v_and_b32_e32 v10, 0xffff, v10
	v_lshl_or_b32 v128, v9, 16, v8
	v_lshl_or_b32 v129, v11, 16, v10
	global_store_dwordx2 v3, v[128:129], s[8:9]
	s_add_u32 s8, s8, 0x100000
	s_addc_u32 s9, s9, 0
	s_waitcnt vmcnt(19)
	v_cvt_pk_fp8_f32 v8, v72, v73
	v_cvt_pk_fp8_f32 v9, v74, v75
	v_cvt_pk_fp8_f32 v10, v76, v77
	v_cvt_pk_fp8_f32 v11, v78, v79
	v_and_b32_e32 v8, 0xffff, v8
	v_and_b32_e32 v10, 0xffff, v10
	v_lshl_or_b32 v130, v9, 16, v8
	v_lshl_or_b32 v131, v11, 16, v10
	global_store_dwordx2 v3, v[130:131], s[8:9]
	s_add_u32 s8, s8, 0x100000
	s_addc_u32 s9, s9, 0
	s_waitcnt vmcnt(17)
	v_cvt_pk_fp8_f32 v8, v80, v81
	v_cvt_pk_fp8_f32 v9, v82, v83
	v_cvt_pk_fp8_f32 v10, v84, v85
	v_cvt_pk_fp8_f32 v11, v86, v87
	v_and_b32_e32 v8, 0xffff, v8
	v_and_b32_e32 v10, 0xffff, v10
	v_lshl_or_b32 v132, v9, 16, v8
	v_lshl_or_b32 v133, v11, 16, v10
	global_store_dwordx2 v3, v[132:133], s[8:9]
	s_add_u32 s8, s8, 0x100000
	s_addc_u32 s9, s9, 0
	s_waitcnt vmcnt(15)
	v_cvt_pk_fp8_f32 v8, v88, v89
	v_cvt_pk_fp8_f32 v9, v90, v91
	v_cvt_pk_fp8_f32 v10, v92, v93
	v_cvt_pk_fp8_f32 v11, v94, v95
	v_and_b32_e32 v8, 0xffff, v8
	v_and_b32_e32 v10, 0xffff, v10
	v_lshl_or_b32 v134, v9, 16, v8
	v_lshl_or_b32 v135, v11, 16, v10
	global_store_dwordx2 v3, v[134:135], s[8:9]
	s_add_u32 s8, s8, 0x100000
	s_addc_u32 s9, s9, 0
	s_waitcnt vmcnt(13)
	v_cvt_pk_fp8_f32 v8, v96, v97
	v_cvt_pk_fp8_f32 v9, v98, v99
	v_cvt_pk_fp8_f32 v10, v100, v101
	v_cvt_pk_fp8_f32 v11, v102, v103
	v_and_b32_e32 v8, 0xffff, v8
	v_and_b32_e32 v10, 0xffff, v10
	v_lshl_or_b32 v136, v9, 16, v8
	v_lshl_or_b32 v137, v11, 16, v10
	global_store_dwordx2 v3, v[136:137], s[8:9]
	s_add_u32 s8, s8, 0x100000
	s_addc_u32 s9, s9, 0
	s_waitcnt vmcnt(11)
; #define LAS __attribute__((address_space(3)))
; __global__ void __launch_bounds__(512, 2) hybrid_fwd(Args a) {
;     ...
;         for (size_t i = gt; i < (size_t)M * 64; i += GT) {
;             const int t = (int)(i >> 6), j = (int)(i & 63);
;             const float ang = (float)a.pos[t] * a.inv_freq[j];
;             const double rev = (double)ang * 0.15915494309189535; const float fr = (float)(rev - __builtin_rint(rev));
;             const f32x2 cs = (f32x2){__builtin_amdgcn_cosf(fr), __builtin_amdgcn_sinf(fr)};
;             csB[i] = cs; if ((j & 1) == 0) csA[(size_t)t * 32 + (j >> 1)] = cs;
;         }
;         LAS float* scr = (LAS float*)(lds + wave * 16384);
;         const int gw = bx * 8 + wave, NGW = G * 8;
;         constexpr int I_IN = (D / 64) * (DIN / 32);
;         for (int it = gw; it < I_IN; it += NGW) { const int nb = it % (DIN / 32), kb = it / (DIN / 32);
;             if ((a.fp8mask >> (nb >> 3)) & 1ull) transpose_item_fp8(a.w_in, DIN, (unsigned char*)WinT, 4096, 0, 64 * kb, gemm_col_to_orig(32 * nb), 32 * nb, W8_SCALE, scr, lane);
	v_cvt_pk_fp8_f32 v8, v104, v105
	v_cvt_pk_fp8_f32 v9, v106, v107
	v_cvt_pk_fp8_f32 v10, v108, v109
	v_cvt_pk_fp8_f32 v11, v110, v111
	v_and_b32_e32 v8, 0xffff, v8
	v_and_b32_e32 v10, 0xffff, v10
	v_lshl_or_b32 v138, v9, 16, v8
	v_lshl_or_b32 v139, v11, 16, v10
	global_store_dwordx2 v3, v[138:139], s[8:9]
	s_add_u32 s8, s8, 0x100000
	s_addc_u32 s9, s9, 0
	s_waitcnt vmcnt(9)
	v_cvt_pk_fp8_f32 v8, v112, v113
	v_cvt_pk_fp8_f32 v9, v114, v115
	v_cvt_pk_fp8_f32 v10, v116, v117
	v_cvt_pk_fp8_f32 v11, v118, v119
	v_and_b32_e32 v8, 0xffff, v8
	v_and_b32_e32 v10, 0xffff, v10
	v_lshl_or_b32 v140, v9, 16, v8
	v_lshl_or_b32 v141, v11, 16, v10
	global_store_dwordx2 v3, v[140:141], s[8:9]
	s_add_u32 s8, s8, 0x100000
	s_addc_u32 s9, s9, 0
	s_waitcnt vmcnt(7)
	v_cvt_pk_fp8_f32 v8, v120, v121
	v_cvt_pk_fp8_f32 v9, v122, v123
	v_cvt_pk_fp8_f32 v10, v124, v125
	v_cvt_pk_fp8_f32 v11, v126, v127
	v_and_b32_e32 v8, 0xffff, v8
	v_and_b32_e32 v10, 0xffff, v10
	v_lshl_or_b32 v142, v9, 16, v8
	v_lshl_or_b32 v143, v11, 16, v10
	global_store_dwordx2 v3, v[142:143], s[8:9]
	s_add_u32 s8, s8, 0x100000
	s_addc_u32 s9, s9, 0
	s_lshr_b32 s10, s33, 6
	s_lshl_b32 s11, s2, 3
	s_add_u32 s10, s10, s11
	s_lshl_b32 s11, s10, 2
	s_add_u32 s24, s20, s11
	s_addc_u32 s25, s21, 0
	s_load_dword s34, s[24:25], 0x0
	s_load_dword s35, s[24:25], 0x2000
	s_load_dword s36, s[24:25], 0x4000
	s_load_dword s37, s[24:25], 0x6000
	s_load_dword s38, s[24:25], 0x8000
	s_load_dword s39, s[24:25], 0xa000
	s_load_dword s40, s[24:25], 0xc000
	s_load_dword s41, s[24:25], 0xe000
	v_lshlrev_b32_e32 v5, 2, v4
	global_load_dword v5, v5, s[70:71] offset:96
	v_lshlrev_b32_e32 v6, 3, v4
	v_lshrrev_b32_e32 v7, 1, v4
	v_lshlrev_b32_e32 v7, 3, v7
	s_lshl_b32 s11, s10, 9
	s_add_u32 s26, s90, s11
	s_addc_u32 s27, s91, 0
	s_add_u32 s26, s26, 0x7c00000
	s_addc_u32 s27, s27, 0
	s_lshl_b32 s11, s10, 8
	s_add_u32 s28, s90, s11
	s_addc_u32 s29, s91, 0
	s_add_u32 s28, s28, 0x8400000
	s_addc_u32 s29, s29, 0
	s_mov_b32 s42, 0x6dc9c883
	s_mov_b32 s43, 0x3fc45f30
	s_waitcnt vmcnt(0) lgkmcnt(0)
	v_cvt_f32_i32_e32 v16, s34
	v_mul_f32_e32 v16, v5, v16
	v_cvt_f64_f32_e32 v[16:17], v16
	v_mul_f64 v[12:13], v[16:17], s[42:43]
	v_rndne_f64_e32 v[12:13], v[12:13]
	v_fma_f64 v[16:17], v[16:17], s[42:43], -v[12:13]
	v_cvt_f32_f64_e32 v17, v[16:17]
	v_cos_f32_e32 v16, v17
	v_sin_f32_e32 v17, v17
	v_cvt_f32_i32_e32 v18, s35
	v_mul_f32_e32 v18, v5, v18
	v_cvt_f64_f32_e32 v[18:19], v18
	v_mul_f64 v[12:13], v[18:19], s[42:43]
	v_rndne_f64_e32 v[12:13], v[12:13]
	v_fma_f64 v[18:19], v[18:19], s[42:43], -v[12:13]
	v_cvt_f32_f64_e32 v19, v[18:19]
	v_cos_f32_e32 v18, v19
	v_sin_f32_e32 v19, v19
	v_cvt_f32_i32_e32 v20, s36
	v_mul_f32_e32 v20, v5, v20
	v_cvt_f64_f32_e32 v[20:21], v20
	v_mul_f64 v[12:13], v[20:21], s[42:43]
	v_rndne_f64_e32 v[12:13], v[12:13]
	v_fma_f64 v[20:21], v[20:21], s[42:43], -v[12:13]
	v_cvt_f32_f64_e32 v21, v[20:21]
	v_cos_f32_e32 v20, v21
	v_sin_f32_e32 v21, v21
	v_cvt_f32_i32_e32 v22, s37
	v_mul_f32_e32 v22, v5, v22
	v_cvt_f64_f32_e32 v[22:23], v22
	v_mul_f64 v[12:13], v[22:23], s[42:43]
	v_rndne_f64_e32 v[12:13], v[12:13]
	v_fma_f64 v[22:23], v[22:23], s[42:43], -v[12:13]
	v_cvt_f32_f64_e32 v23, v[22:23]
	v_cos_f32_e32 v22, v23
	v_sin_f32_e32 v23, v23
	v_cvt_f32_i32_e32 v24, s38
	v_mul_f32_e32 v24, v5, v24
	v_cvt_f64_f32_e32 v[24:25], v24
	v_mul_f64 v[12:13], v[24:25], s[42:43]
	v_rndne_f64_e32 v[12:13], v[12:13]
	v_fma_f64 v[24:25], v[24:25], s[42:43], -v[12:13]
	v_cvt_f32_f64_e32 v25, v[24:25]
	v_cos_f32_e32 v24, v25
	v_sin_f32_e32 v25, v25
	v_cvt_f32_i32_e32 v26, s39
	v_mul_f32_e32 v26, v5, v26
	v_cvt_f64_f32_e32 v[26:27], v26
	v_mul_f64 v[12:13], v[26:27], s[42:43]
	v_rndne_f64_e32 v[12:13], v[12:13]
	v_fma_f64 v[26:27], v[26:27], s[42:43], -v[12:13]
	v_cvt_f32_f64_e32 v27, v[26:27]
	v_cos_f32_e32 v26, v27
	v_sin_f32_e32 v27, v27
	v_cvt_f32_i32_e32 v28, s40
	v_mul_f32_e32 v28, v5, v28
	v_cvt_f64_f32_e32 v[28:29], v28
	v_mul_f64 v[12:13], v[28:29], s[42:43]
	v_rndne_f64_e32 v[12:13], v[12:13]
	v_fma_f64 v[28:29], v[28:29], s[42:43], -v[12:13]
	v_cvt_f32_f64_e32 v29, v[28:29]
	v_cos_f32_e32 v28, v29
	v_sin_f32_e32 v29, v29
	v_cvt_f32_i32_e32 v30, s41
	v_mul_f32_e32 v30, v5, v30
	v_cvt_f64_f32_e32 v[30:31], v30
	v_mul_f64 v[12:13], v[30:31], s[42:43]
	v_rndne_f64_e32 v[12:13], v[12:13]
	v_fma_f64 v[30:31], v[30:31], s[42:43], -v[12:13]
	v_cvt_f32_f64_e32 v31, v[30:31]
	v_cos_f32_e32 v30, v31
	v_sin_f32_e32 v31, v31
	s_nop 1
	global_store_dwordx2 v6, v[16:17], s[26:27]
	s_add_u32 s26, s26, 0x100000
	s_addc_u32 s27, s27, 0
	global_store_dwordx2 v6, v[18:19], s[26:27]
	s_add_u32 s26, s26, 0x100000
	s_addc_u32 s27, s27, 0
	global_store_dwordx2 v6, v[20:21], s[26:27]
	s_add_u32 s26, s26, 0x100000
	s_addc_u32 s27, s27, 0
	global_store_dwordx2 v6, v[22:23], s[26:27]
	s_add_u32 s26, s26, 0x100000
	s_addc_u32 s27, s27, 0
	global_store_dwordx2 v6, v[24:25], s[26:27]
	s_add_u32 s26, s26, 0x100000
	s_addc_u32 s27, s27, 0
	global_store_dwordx2 v6, v[26:27], s[26:27]
	s_add_u32 s26, s26, 0x100000
	s_addc_u32 s27, s27, 0
	global_store_dwordx2 v6, v[28:29], s[26:27]
	s_add_u32 s26, s26, 0x100000
	s_addc_u32 s27, s27, 0
	global_store_dwordx2 v6, v[30:31], s[26:27]
	s_mov_b32 exec_lo, 0x55555555
	s_mov_b32 exec_hi, 0x55555555
	s_nop 1
	global_store_dwordx2 v7, v[16:17], s[28:29]
	s_add_u32 s28, s28, 0x80000
	s_addc_u32 s29, s29, 0
	global_store_dwordx2 v7, v[18:19], s[28:29]
	s_add_u32 s28, s28, 0x80000
	s_addc_u32 s29, s29, 0
	global_store_dwordx2 v7, v[20:21], s[28:29]
	s_add_u32 s28, s28, 0x80000
	s_addc_u32 s29, s29, 0
	global_store_dwordx2 v7, v[22:23], s[28:29]
	s_add_u32 s28, s28, 0x80000
	s_addc_u32 s29, s29, 0
	global_store_dwordx2 v7, v[24:25], s[28:29]
	s_add_u32 s28, s28, 0x80000
	s_addc_u32 s29, s29, 0
	global_store_dwordx2 v7, v[26:27], s[28:29]
	s_add_u32 s28, s28, 0x80000
	s_addc_u32 s29, s29, 0
	global_store_dwordx2 v7, v[28:29], s[28:29]
	s_add_u32 s28, s28, 0x80000
	s_addc_u32 s29, s29, 0
	global_store_dwordx2 v7, v[30:31], s[28:29]
	s_mov_b64 exec, -1
	s_nop 1
	v_and_b32_e32 v12, 7, v4
	v_lshrrev_b32_e32 v13, 3, v4
	v_lshlrev_b32_e32 v14, 4, v12
	s_mov_b32 s10, 0x5a000
	v_mul_lo_u32 v15, v13, s10
	v_add_u32_e32 v162, v15, v14
	v_add_u32_e32 v163, 0xb400, v162
	v_add_u32_e32 v164, 0x16800, v162
	v_add_u32_e32 v165, 0x21c00, v162
	v_add_u32_e32 v166, 0x2d000, v162
	v_add_u32_e32 v167, 0x38400, v162
	v_add_u32_e32 v168, 0x43800, v162
	v_add_u32_e32 v169, 0x4ec00, v162
	v_lshlrev_b32_e32 v14, 14, v12
	v_lshl_add_u32 v170, v13, 3, v14
	v_add_u32_e32 v171, 0x1000, v170
	v_add_u32_e32 v172, 0x2000, v170
	v_add_u32_e32 v173, 0x3000, v170
	s_mov_b32 s44, 0x42800000
	s_mov_b32 s45, 0x42800000
	s_lshr_b32 s10, s33, 6
	s_lshl_b32 s11, s2, 3
	s_add_u32 s46, s10, s11
	s_add_u32 s64, s90, 0x4000000
	s_addc_u32 s65, s91, 0
	s_cmpk_ge_u32 s46, 0x680
	s_cbranch_scc1 .Lp0c_four
; #define LAS __attribute__((address_space(3)))
; __host__ __device__ __forceinline__ int tile_mode(int pn) { return (pn <= 4) ? 1 : (pn >= 9 && pn <= 20) ? 2 : 0; }
; __host__ __device__ __forceinline__ int gemm_col_to_orig(int nprime) {
;     const int pn = nprime >> 8, xp = nprime & 255, bj = xp >> 7, x = xp & 127, md = tile_mode(pn);
;     if (md == 1) return 256 * pn + 64 * (x >> 5) + (x & 31) + 32 * bj;
;     if (md == 2) return 256 * pn + 128 * (x >> 6) + (x & 63) + 64 * bj;
;     return nprime;
; __device__ __forceinline__ void transpose_item_fp8(const float* W, int N, unsigned char* W8, int pitch, int kofs, int k0, int n_src, int n_dst, float scale, LAS float* scr, int lane) {
;     ...
;     for (int i = 0; i < 8; ++i) v[i] = *(const f32x4*)(W + (size_t)(k0 + r8 + 8 * i) * N + n_src + 4 * c4);
; #pragma unroll
;     for (int i = 0; i < 8; ++i) { LAS float* d = scr + (r8 + 8 * i) * 33 + 4 * c4; d[0] = v[i][0]; d[1] = v[i][1]; d[2] = v[i][2]; d[3] = v[i][3]; }
;     asm volatile("s_waitcnt lgkmcnt(0)" ::: "memory");
;     const int n = lane & 31, cp = lane >> 5;
; #pragma unroll
;     for (int q = 0; q < 2; ++q) { const int ck = (2 * cp + q) * 16; const LAS float* sp = scr + ck * 33 + n; u32x4 o;
; #pragma unroll
;         for (int w = 0; w < 4; ++w) o[w] = pack_fp8x4(sp[(4 * w) * 33] * scale, sp[(4 * w + 1) * 33] * scale, sp[(4 * w + 2) * 33] * scale, sp[(4 * w + 3) * 33] * scale);
;         *(u32x4*)(W8 + (size_t)(n_dst + n) * pitch + kofs + k0 + ck) = o; }
	s_add_u32 s47, s46, 0x0
	s_mul_hi_u32 s48, s47, 0xb60b61
	s_mul_i32 s49, s48, 0x168
	s_sub_u32 s49, s47, s49
	s_lshl_b32 s50, s48, 1
	s_lshr_b32 s51, s49, 3
	s_and_b32 s52, s49, 7
	s_and_b32 s53, s52, 3
	s_lshr_b32 s54, s52, 2
	s_lshl_b32 s55, s53, 6
	s_lshl_b32 s56, s54, 5
	s_add_u32 s55, s55, s56
	s_bfe_u32 s56, s52, 0x10001
	s_lshl_b32 s56, s56, 7
	s_and_b32 s57, s52, 1
	s_lshl_b32 s57, s57, 5
	s_add_u32 s56, s56, s57
	s_lshl_b32 s57, s54, 6
	s_add_u32 s56, s56, s57
	s_lshl_b32 s57, s52, 5
	s_sub_u32 s58, s51, 9
	s_cmp_lt_u32 s58, 12
	s_cselect_b32 s57, s56, s57
	s_cmp_lt_u32 s51, 5
	s_cselect_b32 s57, s55, s57
	s_lshl_b32 s58, s51, 8
	s_add_u32 s57, s57, s58
	s_mul_i32 s58, s50, 0x2d0000
	s_lshl_b32 s57, s57, 2
	s_add_u32 s58, s58, s57
	s_add_u32 s60, s22, s58
	s_addc_u32 s61, s23, 0
	s_lshl_b32 s58, s49, 17
	s_lshl_b32 s59, s50, 6
	s_add_u32 s58, s58, s59
	s_add_u32 s74, s64, s58
	s_addc_u32 s75, s65, 0
	global_load_dwordx4 v[64:67], v162, s[60:61] nt
	global_load_dwordx4 v[68:71], v163, s[60:61] nt
	global_load_dwordx4 v[72:75], v164, s[60:61] nt
	global_load_dwordx4 v[76:79], v165, s[60:61] nt
	global_load_dwordx4 v[80:83], v166, s[60:61] nt
	global_load_dwordx4 v[84:87], v167, s[60:61] nt
	global_load_dwordx4 v[88:91], v168, s[60:61] nt
	global_load_dwordx4 v[92:95], v169, s[60:61] nt
	s_add_u32 s47, s46, 0x0
	s_mul_hi_u32 s48, s47, 0xb60b61
	s_mul_i32 s49, s48, 0x168
	s_sub_u32 s49, s47, s49
	s_lshl_b32 s50, s48, 1
	s_or_b32 s50, s50, 1
	s_lshr_b32 s51, s49, 3
	s_and_b32 s52, s49, 7
	s_and_b32 s53, s52, 3
	s_lshr_b32 s54, s52, 2
	s_lshl_b32 s55, s53, 6
	s_lshl_b32 s56, s54, 5
	s_add_u32 s55, s55, s56
	s_bfe_u32 s56, s52, 0x10001
	s_lshl_b32 s56, s56, 7
	s_and_b32 s57, s52, 1
	s_lshl_b32 s57, s57, 5
	s_add_u32 s56, s56, s57
	s_lshl_b32 s57, s54, 6
	s_add_u32 s56, s56, s57
	s_lshl_b32 s57, s52, 5
	s_sub_u32 s58, s51, 9
	s_cmp_lt_u32 s58, 12
	s_cselect_b32 s57, s56, s57
	s_cmp_lt_u32 s51, 5
	s_cselect_b32 s57, s55, s57
	s_lshl_b32 s58, s51, 8
	s_add_u32 s57, s57, s58
	s_mul_i32 s58, s50, 0x2d0000
	s_lshl_b32 s57, s57, 2
	s_add_u32 s58, s58, s57
	s_add_u32 s60, s22, s58
	s_addc_u32 s61, s23, 0
	s_lshl_b32 s58, s49, 17
	s_lshl_b32 s59, s50, 6
	s_add_u32 s58, s58, s59
	s_add_u32 s76, s64, s58
	s_addc_u32 s77, s65, 0
	global_load_dwordx4 v[96:99], v162, s[60:61] nt
	global_load_dwordx4 v[100:103], v163, s[60:61] nt
	global_load_dwordx4 v[104:107], v164, s[60:61] nt
	global_load_dwordx4 v[108:111], v165, s[60:61] nt
	global_load_dwordx4 v[112:115], v166, s[60:61] nt
	global_load_dwordx4 v[116:119], v167, s[60:61] nt
	global_load_dwordx4 v[120:123], v168, s[60:61] nt
	global_load_dwordx4 v[124:127], v169, s[60:61] nt
	s_add_u32 s47, s46, 0x800
	s_mul_hi_u32 s48, s47, 0xb60b61
	s_mul_i32 s49, s48, 0x168
	s_sub_u32 s49, s47, s49
	s_lshl_b32 s50, s48, 1
	s_lshr_b32 s51, s49, 3
	s_and_b32 s52, s49, 7
	s_and_b32 s53, s52, 3
	s_lshr_b32 s54, s52, 2
	s_lshl_b32 s55, s53, 6
	s_lshl_b32 s56, s54, 5
	s_add_u32 s55, s55, s56
	s_bfe_u32 s56, s52, 0x10001
	s_lshl_b32 s56, s56, 7
	s_and_b32 s57, s52, 1
	s_lshl_b32 s57, s57, 5
	s_add_u32 s56, s56, s57
	s_lshl_b32 s57, s54, 6
	s_add_u32 s56, s56, s57
	s_lshl_b32 s57, s52, 5
	s_sub_u32 s58, s51, 9
	s_cmp_lt_u32 s58, 12
	s_cselect_b32 s57, s56, s57
	s_cmp_lt_u32 s51, 5
	s_cselect_b32 s57, s55, s57
	s_lshl_b32 s58, s51, 8
	s_add_u32 s57, s57, s58
	s_mul_i32 s58, s50, 0x2d0000
	s_lshl_b32 s57, s57, 2
	s_add_u32 s58, s58, s57
	s_add_u32 s60, s22, s58
	s_addc_u32 s61, s23, 0
	s_lshl_b32 s58, s49, 17
	s_lshl_b32 s59, s50, 6
	s_add_u32 s58, s58, s59
	s_add_u32 s78, s64, s58
	s_addc_u32 s79, s65, 0
	global_load_dwordx4 v[128:131], v162, s[60:61] nt
	global_load_dwordx4 v[132:135], v163, s[60:61] nt
	global_load_dwordx4 v[136:139], v164, s[60:61] nt
	global_load_dwordx4 v[140:143], v165, s[60:61] nt
	global_load_dwordx4 v[144:147], v166, s[60:61] nt
	global_load_dwordx4 v[148:151], v167, s[60:61] nt
	global_load_dwordx4 v[152:155], v168, s[60:61] nt
	global_load_dwordx4 v[156:159], v169, s[60:61] nt
	s_waitcnt vmcnt(16)
	v_pk_mul_f32 v[64:65], v[64:65], s[44:45]
	v_pk_mul_f32 v[66:67], v[66:67], s[44:45]
	v_pk_mul_f32 v[68:69], v[68:69], s[44:45]
	v_pk_mul_f32 v[70:71], v[70:71], s[44:45]
	v_pk_mul_f32 v[72:73], v[72:73], s[44:45]
	v_pk_mul_f32 v[74:75], v[74:75], s[44:45]
	v_pk_mul_f32 v[76:77], v[76:77], s[44:45]
	v_pk_mul_f32 v[78:79], v[78:79], s[44:45]
	v_pk_mul_f32 v[80:81], v[80:81], s[44:45]
	v_pk_mul_f32 v[82:83], v[82:83], s[44:45]
	v_pk_mul_f32 v[84:85], v[84:85], s[44:45]
	v_pk_mul_f32 v[86:87], v[86:87], s[44:45]
	v_pk_mul_f32 v[88:89], v[88:89], s[44:45]
	v_pk_mul_f32 v[90:91], v[90:91], s[44:45]
	v_pk_mul_f32 v[92:93], v[92:93], s[44:45]
	v_pk_mul_f32 v[94:95], v[94:95], s[44:45]
	v_cvt_pk_fp8_f32 v8, v64, v68
	v_cvt_pk_fp8_f32 v9, v72, v76
	v_cvt_pk_fp8_f32 v10, v80, v84
	v_cvt_pk_fp8_f32 v11, v88, v92
	v_and_b32_e32 v8, 0xffff, v8
	v_and_b32_e32 v10, 0xffff, v10
	v_lshl_or_b32 v176, v9, 16, v8
	v_lshl_or_b32 v177, v11, 16, v10
	global_store_dwordx2 v170, v[176:177], s[74:75]
	v_cvt_pk_fp8_f32 v8, v65, v69
	v_cvt_pk_fp8_f32 v9, v73, v77
	v_cvt_pk_fp8_f32 v10, v81, v85
	v_cvt_pk_fp8_f32 v11, v89, v93
	v_and_b32_e32 v8, 0xffff, v8
	v_and_b32_e32 v10, 0xffff, v10
	v_lshl_or_b32 v178, v9, 16, v8
	v_lshl_or_b32 v179, v11, 16, v10
	global_store_dwordx2 v171, v[178:179], s[74:75]
	v_cvt_pk_fp8_f32 v8, v66, v70
	v_cvt_pk_fp8_f32 v9, v74, v78
	v_cvt_pk_fp8_f32 v10, v82, v86
	v_cvt_pk_fp8_f32 v11, v90, v94
	v_and_b32_e32 v8, 0xffff, v8
	v_and_b32_e32 v10, 0xffff, v10
	v_lshl_or_b32 v180, v9, 16, v8
	v_lshl_or_b32 v181, v11, 16, v10
	global_store_dwordx2 v172, v[180:181], s[74:75]
	v_cvt_pk_fp8_f32 v8, v67, v71
; #define LAS __attribute__((address_space(3)))
; __device__ __forceinline__ void transpose_item_fp8(const float* W, int N, unsigned char* W8, int pitch, int kofs, int k0, int n_src, int n_dst, float scale, LAS float* scr, int lane) {
;     ...
;     for (int i = 0; i < 8; ++i) v[i] = *(const f32x4*)(W + (size_t)(k0 + r8 + 8 * i) * N + n_src + 4 * c4);
; #pragma unroll
;     for (int i = 0; i < 8; ++i) { LAS float* d = scr + (r8 + 8 * i) * 33 + 4 * c4; d[0] = v[i][0]; d[1] = v[i][1]; d[2] = v[i][2]; d[3] = v[i][3]; }
;     asm volatile("s_waitcnt lgkmcnt(0)" ::: "memory");
;     const int n = lane & 31, cp = lane >> 5;
; #pragma unroll
;     for (int q = 0; q < 2; ++q) { const int ck = (2 * cp + q) * 16; const LAS float* sp = scr + ck * 33 + n; u32x4 o;
; #pragma unroll
;         for (int w = 0; w < 4; ++w) o[w] = pack_fp8x4(sp[(4 * w) * 33] * scale, sp[(4 * w + 1) * 33] * scale, sp[(4 * w + 2) * 33] * scale, sp[(4 * w + 3) * 33] * scale);
;         *(u32x4*)(W8 + (size_t)(n_dst + n) * pitch + kofs + k0 + ck) = o; }
	v_cvt_pk_fp8_f32 v9, v75, v79
	v_cvt_pk_fp8_f32 v10, v83, v87
	v_cvt_pk_fp8_f32 v11, v91, v95
	v_and_b32_e32 v8, 0xffff, v8
	v_and_b32_e32 v10, 0xffff, v10
	v_lshl_or_b32 v182, v9, 16, v8
	v_lshl_or_b32 v183, v11, 16, v10
	global_store_dwordx2 v173, v[182:183], s[74:75]
	s_add_u32 s47, s46, 0x800
	s_mul_hi_u32 s48, s47, 0xb60b61
	s_mul_i32 s49, s48, 0x168
	s_sub_u32 s49, s47, s49
	s_lshl_b32 s50, s48, 1
	s_or_b32 s50, s50, 1
	s_lshr_b32 s51, s49, 3
	s_and_b32 s52, s49, 7
	s_and_b32 s53, s52, 3
	s_lshr_b32 s54, s52, 2
	s_lshl_b32 s55, s53, 6
	s_lshl_b32 s56, s54, 5
	s_add_u32 s55, s55, s56
	s_bfe_u32 s56, s52, 0x10001
	s_lshl_b32 s56, s56, 7
	s_and_b32 s57, s52, 1
	s_lshl_b32 s57, s57, 5
	s_add_u32 s56, s56, s57
	s_lshl_b32 s57, s54, 6
	s_add_u32 s56, s56, s57
	s_lshl_b32 s57, s52, 5
	s_sub_u32 s58, s51, 9
	s_cmp_lt_u32 s58, 12
	s_cselect_b32 s57, s56, s57
	s_cmp_lt_u32 s51, 5
	s_cselect_b32 s57, s55, s57
	s_lshl_b32 s58, s51, 8
	s_add_u32 s57, s57, s58
	s_mul_i32 s58, s50, 0x2d0000
	s_lshl_b32 s57, s57, 2
	s_add_u32 s58, s58, s57
	s_add_u32 s60, s22, s58
	s_addc_u32 s61, s23, 0
	s_lshl_b32 s58, s49, 17
	s_lshl_b32 s59, s50, 6
	s_add_u32 s58, s58, s59
	s_add_u32 s74, s64, s58
	s_addc_u32 s75, s65, 0
	global_load_dwordx4 v[64:67], v162, s[60:61] nt
	global_load_dwordx4 v[68:71], v163, s[60:61] nt
	global_load_dwordx4 v[72:75], v164, s[60:61] nt
	global_load_dwordx4 v[76:79], v165, s[60:61] nt
	global_load_dwordx4 v[80:83], v166, s[60:61] nt
	global_load_dwordx4 v[84:87], v167, s[60:61] nt
	global_load_dwordx4 v[88:91], v168, s[60:61] nt
	global_load_dwordx4 v[92:95], v169, s[60:61] nt
	s_waitcnt vmcnt(20)
	v_pk_mul_f32 v[96:97], v[96:97], s[44:45]
	v_pk_mul_f32 v[98:99], v[98:99], s[44:45]
	v_pk_mul_f32 v[100:101], v[100:101], s[44:45]
	v_pk_mul_f32 v[102:103], v[102:103], s[44:45]
	v_pk_mul_f32 v[104:105], v[104:105], s[44:45]
	v_pk_mul_f32 v[106:107], v[106:107], s[44:45]
	v_pk_mul_f32 v[108:109], v[108:109], s[44:45]
	v_pk_mul_f32 v[110:111], v[110:111], s[44:45]
	v_pk_mul_f32 v[112:113], v[112:113], s[44:45]
	v_pk_mul_f32 v[114:115], v[114:115], s[44:45]
	v_pk_mul_f32 v[116:117], v[116:117], s[44:45]
	v_pk_mul_f32 v[118:119], v[118:119], s[44:45]
	v_pk_mul_f32 v[120:121], v[120:121], s[44:45]
	v_pk_mul_f32 v[122:123], v[122:123], s[44:45]
	v_pk_mul_f32 v[124:125], v[124:125], s[44:45]
	v_pk_mul_f32 v[126:127], v[126:127], s[44:45]
	v_cvt_pk_fp8_f32 v8, v96, v100
	v_cvt_pk_fp8_f32 v9, v104, v108
	v_cvt_pk_fp8_f32 v10, v112, v116
	v_cvt_pk_fp8_f32 v11, v120, v124
	v_and_b32_e32 v8, 0xffff, v8
	v_and_b32_e32 v10, 0xffff, v10
	v_lshl_or_b32 v184, v9, 16, v8
	v_lshl_or_b32 v185, v11, 16, v10
	global_store_dwordx2 v170, v[184:185], s[76:77]
	v_cvt_pk_fp8_f32 v8, v97, v101
	v_cvt_pk_fp8_f32 v9, v105, v109
	v_cvt_pk_fp8_f32 v10, v113, v117
	v_cvt_pk_fp8_f32 v11, v121, v125
	v_and_b32_e32 v8, 0xffff, v8
	v_and_b32_e32 v10, 0xffff, v10
	v_lshl_or_b32 v186, v9, 16, v8
	v_lshl_or_b32 v187, v11, 16, v10
	global_store_dwordx2 v171, v[186:187], s[76:77]
	v_cvt_pk_fp8_f32 v8, v98, v102
	v_cvt_pk_fp8_f32 v9, v106, v110
	v_cvt_pk_fp8_f32 v10, v114, v118
	v_cvt_pk_fp8_f32 v11, v122, v126
	v_and_b32_e32 v8, 0xffff, v8
	v_and_b32_e32 v10, 0xffff, v10
	v_lshl_or_b32 v188, v9, 16, v8
	v_lshl_or_b32 v189, v11, 16, v10
	global_store_dwordx2 v172, v[188:189], s[76:77]
	v_cvt_pk_fp8_f32 v8, v99, v103
	v_cvt_pk_fp8_f32 v9, v107, v111
	v_cvt_pk_fp8_f32 v10, v115, v119
	v_cvt_pk_fp8_f32 v11, v123, v127
	v_and_b32_e32 v8, 0xffff, v8
	v_and_b32_e32 v10, 0xffff, v10
	v_lshl_or_b32 v190, v9, 16, v8
	v_lshl_or_b32 v191, v11, 16, v10
	global_store_dwordx2 v173, v[190:191], s[76:77]
	s_add_u32 s47, s46, 0x1000
	s_mul_hi_u32 s48, s47, 0xb60b61
	s_mul_i32 s49, s48, 0x168
	s_sub_u32 s49, s47, s49
	s_lshl_b32 s50, s48, 1
	s_lshr_b32 s51, s49, 3
	s_and_b32 s52, s49, 7
	s_and_b32 s53, s52, 3
	s_lshr_b32 s54, s52, 2
	s_lshl_b32 s55, s53, 6
	s_lshl_b32 s56, s54, 5
	s_add_u32 s55, s55, s56
	s_bfe_u32 s56, s52, 0x10001
	s_lshl_b32 s56, s56, 7
	s_and_b32 s57, s52, 1
	s_lshl_b32 s57, s57, 5
	s_add_u32 s56, s56, s57
	s_lshl_b32 s57, s54, 6
	s_add_u32 s56, s56, s57
	s_lshl_b32 s57, s52, 5
	s_sub_u32 s58, s51, 9
	s_cmp_lt_u32 s58, 12
	s_cselect_b32 s57, s56, s57
	s_cmp_lt_u32 s51, 5
	s_cselect_b32 s57, s55, s57
	s_lshl_b32 s58, s51, 8
	s_add_u32 s57, s57, s58
	s_mul_i32 s58, s50, 0x2d0000
	s_lshl_b32 s57, s57, 2
	s_add_u32 s58, s58, s57
	s_add_u32 s60, s22, s58
	s_addc_u32 s61, s23, 0
	s_lshl_b32 s58, s49, 17
	s_lshl_b32 s59, s50, 6
	s_add_u32 s58, s58, s59
	s_add_u32 s76, s64, s58
	s_addc_u32 s77, s65, 0
	global_load_dwordx4 v[96:99], v162, s[60:61] nt
	global_load_dwordx4 v[100:103], v163, s[60:61] nt
	global_load_dwordx4 v[104:107], v164, s[60:61] nt
	global_load_dwordx4 v[108:111], v165, s[60:61] nt
	global_load_dwordx4 v[112:115], v166, s[60:61] nt
	global_load_dwordx4 v[116:119], v167, s[60:61] nt
	global_load_dwordx4 v[120:123], v168, s[60:61] nt
	global_load_dwordx4 v[124:127], v169, s[60:61] nt
	s_waitcnt vmcnt(24)
; #define LAS __attribute__((address_space(3)))
; __device__ __forceinline__ void transpose_item_fp8(const float* W, int N, unsigned char* W8, int pitch, int kofs, int k0, int n_src, int n_dst, float scale, LAS float* scr, int lane) {
;     ...
;     for (int i = 0; i < 8; ++i) v[i] = *(const f32x4*)(W + (size_t)(k0 + r8 + 8 * i) * N + n_src + 4 * c4);
; #pragma unroll
;     for (int i = 0; i < 8; ++i) { LAS float* d = scr + (r8 + 8 * i) * 33 + 4 * c4; d[0] = v[i][0]; d[1] = v[i][1]; d[2] = v[i][2]; d[3] = v[i][3]; }
;     asm volatile("s_waitcnt lgkmcnt(0)" ::: "memory");
;     const int n = lane & 31, cp = lane >> 5;
; #pragma unroll
;     for (int q = 0; q < 2; ++q) { const int ck = (2 * cp + q) * 16; const LAS float* sp = scr + ck * 33 + n; u32x4 o;
; #pragma unroll
;         for (int w = 0; w < 4; ++w) o[w] = pack_fp8x4(sp[(4 * w) * 33] * scale, sp[(4 * w + 1) * 33] * scale, sp[(4 * w + 2) * 33] * scale, sp[(4 * w + 3) * 33] * scale);
;         *(u32x4*)(W8 + (size_t)(n_dst + n) * pitch + kofs + k0 + ck) = o; }
	v_pk_mul_f32 v[128:129], v[128:129], s[44:45]
	v_pk_mul_f32 v[130:131], v[130:131], s[44:45]
	v_pk_mul_f32 v[132:133], v[132:133], s[44:45]
	v_pk_mul_f32 v[134:135], v[134:135], s[44:45]
	v_pk_mul_f32 v[136:137], v[136:137], s[44:45]
	v_pk_mul_f32 v[138:139], v[138:139], s[44:45]
	v_pk_mul_f32 v[140:141], v[140:141], s[44:45]
	v_pk_mul_f32 v[142:143], v[142:143], s[44:45]
	v_pk_mul_f32 v[144:145], v[144:145], s[44:45]
	v_pk_mul_f32 v[146:147], v[146:147], s[44:45]
	v_pk_mul_f32 v[148:149], v[148:149], s[44:45]
	v_pk_mul_f32 v[150:151], v[150:151], s[44:45]
	v_pk_mul_f32 v[152:153], v[152:153], s[44:45]
	v_pk_mul_f32 v[154:155], v[154:155], s[44:45]
	v_pk_mul_f32 v[156:157], v[156:157], s[44:45]
	v_pk_mul_f32 v[158:159], v[158:159], s[44:45]
	v_cvt_pk_fp8_f32 v8, v128, v132
	v_cvt_pk_fp8_f32 v9, v136, v140
	v_cvt_pk_fp8_f32 v10, v144, v148
	v_cvt_pk_fp8_f32 v11, v152, v156
	v_and_b32_e32 v8, 0xffff, v8
	v_and_b32_e32 v10, 0xffff, v10
	v_lshl_or_b32 v176, v9, 16, v8
	v_lshl_or_b32 v177, v11, 16, v10
	global_store_dwordx2 v170, v[176:177], s[78:79]
	v_cvt_pk_fp8_f32 v8, v129, v133
	v_cvt_pk_fp8_f32 v9, v137, v141
	v_cvt_pk_fp8_f32 v10, v145, v149
	v_cvt_pk_fp8_f32 v11, v153, v157
	v_and_b32_e32 v8, 0xffff, v8
	v_and_b32_e32 v10, 0xffff, v10
	v_lshl_or_b32 v178, v9, 16, v8
	v_lshl_or_b32 v179, v11, 16, v10
	global_store_dwordx2 v171, v[178:179], s[78:79]
	v_cvt_pk_fp8_f32 v8, v130, v134
	v_cvt_pk_fp8_f32 v9, v138, v142
	v_cvt_pk_fp8_f32 v10, v146, v150
	v_cvt_pk_fp8_f32 v11, v154, v158
	v_and_b32_e32 v8, 0xffff, v8
	v_and_b32_e32 v10, 0xffff, v10
	v_lshl_or_b32 v180, v9, 16, v8
	v_lshl_or_b32 v181, v11, 16, v10
	global_store_dwordx2 v172, v[180:181], s[78:79]
	v_cvt_pk_fp8_f32 v8, v131, v135
	v_cvt_pk_fp8_f32 v9, v139, v143
	v_cvt_pk_fp8_f32 v10, v147, v151
	v_cvt_pk_fp8_f32 v11, v155, v159
	v_and_b32_e32 v8, 0xffff, v8
	v_and_b32_e32 v10, 0xffff, v10
	v_lshl_or_b32 v182, v9, 16, v8
	v_lshl_or_b32 v183, v11, 16, v10
	global_store_dwordx2 v173, v[182:183], s[78:79]
	s_add_u32 s47, s46, 0x1000
	s_mul_hi_u32 s48, s47, 0xb60b61
	s_mul_i32 s49, s48, 0x168
	s_sub_u32 s49, s47, s49
	s_lshl_b32 s50, s48, 1
	s_or_b32 s50, s50, 1
	s_lshr_b32 s51, s49, 3
	s_and_b32 s52, s49, 7
	s_and_b32 s53, s52, 3
	s_lshr_b32 s54, s52, 2
	s_lshl_b32 s55, s53, 6
	s_lshl_b32 s56, s54, 5
	s_add_u32 s55, s55, s56
	s_bfe_u32 s56, s52, 0x10001
	s_lshl_b32 s56, s56, 7
	s_and_b32 s57, s52, 1
	s_lshl_b32 s57, s57, 5
	s_add_u32 s56, s56, s57
	s_lshl_b32 s57, s54, 6
	s_add_u32 s56, s56, s57
	s_lshl_b32 s57, s52, 5
	s_sub_u32 s58, s51, 9
	s_cmp_lt_u32 s58, 12
	s_cselect_b32 s57, s56, s57
	s_cmp_lt_u32 s51, 5
	s_cselect_b32 s57, s55, s57
	s_lshl_b32 s58, s51, 8
	s_add_u32 s57, s57, s58
	s_mul_i32 s58, s50, 0x2d0000
	s_lshl_b32 s57, s57, 2
	s_add_u32 s58, s58, s57
	s_add_u32 s60, s22, s58
	s_addc_u32 s61, s23, 0
	s_lshl_b32 s58, s49, 17
	s_lshl_b32 s59, s50, 6
	s_add_u32 s58, s58, s59
	s_add_u32 s78, s64, s58
	s_addc_u32 s79, s65, 0
	global_load_dwordx4 v[128:131], v162, s[60:61] nt
	global_load_dwordx4 v[132:135], v163, s[60:61] nt
	global_load_dwordx4 v[136:139], v164, s[60:61] nt
	global_load_dwordx4 v[140:143], v165, s[60:61] nt
	global_load_dwordx4 v[144:147], v166, s[60:61] nt
	global_load_dwordx4 v[148:151], v167, s[60:61] nt
	global_load_dwordx4 v[152:155], v168, s[60:61] nt
	global_load_dwordx4 v[156:159], v169, s[60:61] nt
	s_waitcnt vmcnt(24)
	v_pk_mul_f32 v[64:65], v[64:65], s[44:45]
	v_pk_mul_f32 v[66:67], v[66:67], s[44:45]
	v_pk_mul_f32 v[68:69], v[68:69], s[44:45]
	v_pk_mul_f32 v[70:71], v[70:71], s[44:45]
	v_pk_mul_f32 v[72:73], v[72:73], s[44:45]
	v_pk_mul_f32 v[74:75], v[74:75], s[44:45]
	v_pk_mul_f32 v[76:77], v[76:77], s[44:45]
	v_pk_mul_f32 v[78:79], v[78:79], s[44:45]
	v_pk_mul_f32 v[80:81], v[80:81], s[44:45]
	v_pk_mul_f32 v[82:83], v[82:83], s[44:45]
	v_pk_mul_f32 v[84:85], v[84:85], s[44:45]
	v_pk_mul_f32 v[86:87], v[86:87], s[44:45]
	v_pk_mul_f32 v[88:89], v[88:89], s[44:45]
	v_pk_mul_f32 v[90:91], v[90:91], s[44:45]
	v_pk_mul_f32 v[92:93], v[92:93], s[44:45]
	v_pk_mul_f32 v[94:95], v[94:95], s[44:45]
	v_cvt_pk_fp8_f32 v8, v64, v68
	v_cvt_pk_fp8_f32 v9, v72, v76
	v_cvt_pk_fp8_f32 v10, v80, v84
	v_cvt_pk_fp8_f32 v11, v88, v92
	v_and_b32_e32 v8, 0xffff, v8
	v_and_b32_e32 v10, 0xffff, v10
	v_lshl_or_b32 v184, v9, 16, v8
	v_lshl_or_b32 v185, v11, 16, v10
	global_store_dwordx2 v170, v[184:185], s[74:75]
	v_cvt_pk_fp8_f32 v8, v65, v69
	v_cvt_pk_fp8_f32 v9, v73, v77
	v_cvt_pk_fp8_f32 v10, v81, v85
	v_cvt_pk_fp8_f32 v11, v89, v93
	v_and_b32_e32 v8, 0xffff, v8
	v_and_b32_e32 v10, 0xffff, v10
	v_lshl_or_b32 v186, v9, 16, v8
	v_lshl_or_b32 v187, v11, 16, v10
	global_store_dwordx2 v171, v[186:187], s[74:75]
	v_cvt_pk_fp8_f32 v8, v66, v70
	v_cvt_pk_fp8_f32 v9, v74, v78
	v_cvt_pk_fp8_f32 v10, v82, v86
	v_cvt_pk_fp8_f32 v11, v90, v94
	v_and_b32_e32 v8, 0xffff, v8
	v_and_b32_e32 v10, 0xffff, v10
	v_lshl_or_b32 v188, v9, 16, v8
	v_lshl_or_b32 v189, v11, 16, v10
	global_store_dwordx2 v172, v[188:189], s[74:75]
	v_cvt_pk_fp8_f32 v8, v67, v71
	v_cvt_pk_fp8_f32 v9, v75, v79
	v_cvt_pk_fp8_f32 v10, v83, v87
	v_cvt_pk_fp8_f32 v11, v91, v95
	v_and_b32_e32 v8, 0xffff, v8
	v_and_b32_e32 v10, 0xffff, v10
	v_lshl_or_b32 v190, v9, 16, v8
	v_lshl_or_b32 v191, v11, 16, v10
	global_store_dwordx2 v173, v[190:191], s[74:75]
	s_waitcnt vmcnt(16)
; #define LAS __attribute__((address_space(3)))
; __device__ __forceinline__ void transpose_item_fp8(const float* W, int N, unsigned char* W8, int pitch, int kofs, int k0, int n_src, int n_dst, float scale, LAS float* scr, int lane) {
;     ...
;     for (int i = 0; i < 8; ++i) v[i] = *(const f32x4*)(W + (size_t)(k0 + r8 + 8 * i) * N + n_src + 4 * c4);
; #pragma unroll
;     for (int i = 0; i < 8; ++i) { LAS float* d = scr + (r8 + 8 * i) * 33 + 4 * c4; d[0] = v[i][0]; d[1] = v[i][1]; d[2] = v[i][2]; d[3] = v[i][3]; }
;     asm volatile("s_waitcnt lgkmcnt(0)" ::: "memory");
;     const int n = lane & 31, cp = lane >> 5;
; #pragma unroll
;     for (int q = 0; q < 2; ++q) { const int ck = (2 * cp + q) * 16; const LAS float* sp = scr + ck * 33 + n; u32x4 o;
; #pragma unroll
;         for (int w = 0; w < 4; ++w) o[w] = pack_fp8x4(sp[(4 * w) * 33] * scale, sp[(4 * w + 1) * 33] * scale, sp[(4 * w + 2) * 33] * scale, sp[(4 * w + 3) * 33] * scale);
;         *(u32x4*)(W8 + (size_t)(n_dst + n) * pitch + kofs + k0 + ck) = o; }
	v_pk_mul_f32 v[96:97], v[96:97], s[44:45]
	v_pk_mul_f32 v[98:99], v[98:99], s[44:45]
	v_pk_mul_f32 v[100:101], v[100:101], s[44:45]
	v_pk_mul_f32 v[102:103], v[102:103], s[44:45]
	v_pk_mul_f32 v[104:105], v[104:105], s[44:45]
	v_pk_mul_f32 v[106:107], v[106:107], s[44:45]
	v_pk_mul_f32 v[108:109], v[108:109], s[44:45]
	v_pk_mul_f32 v[110:111], v[110:111], s[44:45]
	v_pk_mul_f32 v[112:113], v[112:113], s[44:45]
	v_pk_mul_f32 v[114:115], v[114:115], s[44:45]
	v_pk_mul_f32 v[116:117], v[116:117], s[44:45]
	v_pk_mul_f32 v[118:119], v[118:119], s[44:45]
	v_pk_mul_f32 v[120:121], v[120:121], s[44:45]
	v_pk_mul_f32 v[122:123], v[122:123], s[44:45]
	v_pk_mul_f32 v[124:125], v[124:125], s[44:45]
	v_pk_mul_f32 v[126:127], v[126:127], s[44:45]
	v_cvt_pk_fp8_f32 v8, v96, v100
	v_cvt_pk_fp8_f32 v9, v104, v108
	v_cvt_pk_fp8_f32 v10, v112, v116
	v_cvt_pk_fp8_f32 v11, v120, v124
	v_and_b32_e32 v8, 0xffff, v8
	v_and_b32_e32 v10, 0xffff, v10
	v_lshl_or_b32 v176, v9, 16, v8
	v_lshl_or_b32 v177, v11, 16, v10
	global_store_dwordx2 v170, v[176:177], s[76:77]
	v_cvt_pk_fp8_f32 v8, v97, v101
	v_cvt_pk_fp8_f32 v9, v105, v109
	v_cvt_pk_fp8_f32 v10, v113, v117
	v_cvt_pk_fp8_f32 v11, v121, v125
	v_and_b32_e32 v8, 0xffff, v8
	v_and_b32_e32 v10, 0xffff, v10
	v_lshl_or_b32 v178, v9, 16, v8
	v_lshl_or_b32 v179, v11, 16, v10
	global_store_dwordx2 v171, v[178:179], s[76:77]
	v_cvt_pk_fp8_f32 v8, v98, v102
	v_cvt_pk_fp8_f32 v9, v106, v110
	v_cvt_pk_fp8_f32 v10, v114, v118
	v_cvt_pk_fp8_f32 v11, v122, v126
	v_and_b32_e32 v8, 0xffff, v8
	v_and_b32_e32 v10, 0xffff, v10
	v_lshl_or_b32 v180, v9, 16, v8
	v_lshl_or_b32 v181, v11, 16, v10
	global_store_dwordx2 v172, v[180:181], s[76:77]
	v_cvt_pk_fp8_f32 v8, v99, v103
	v_cvt_pk_fp8_f32 v9, v107, v111
	v_cvt_pk_fp8_f32 v10, v115, v119
	v_cvt_pk_fp8_f32 v11, v123, v127
	v_and_b32_e32 v8, 0xffff, v8
	v_and_b32_e32 v10, 0xffff, v10
	v_lshl_or_b32 v182, v9, 16, v8
	v_lshl_or_b32 v183, v11, 16, v10
	global_store_dwordx2 v173, v[182:183], s[76:77]
	s_waitcnt vmcnt(8)
	v_pk_mul_f32 v[128:129], v[128:129], s[44:45]
	v_pk_mul_f32 v[130:131], v[130:131], s[44:45]
	v_pk_mul_f32 v[132:133], v[132:133], s[44:45]
	v_pk_mul_f32 v[134:135], v[134:135], s[44:45]
	v_pk_mul_f32 v[136:137], v[136:137], s[44:45]
	v_pk_mul_f32 v[138:139], v[138:139], s[44:45]
	v_pk_mul_f32 v[140:141], v[140:141], s[44:45]
	v_pk_mul_f32 v[142:143], v[142:143], s[44:45]
	v_pk_mul_f32 v[144:145], v[144:145], s[44:45]
	v_pk_mul_f32 v[146:147], v[146:147], s[44:45]
	v_pk_mul_f32 v[148:149], v[148:149], s[44:45]
	v_pk_mul_f32 v[150:151], v[150:151], s[44:45]
	v_pk_mul_f32 v[152:153], v[152:153], s[44:45]
	v_pk_mul_f32 v[154:155], v[154:155], s[44:45]
	v_pk_mul_f32 v[156:157], v[156:157], s[44:45]
	v_pk_mul_f32 v[158:159], v[158:159], s[44:45]
	v_cvt_pk_fp8_f32 v8, v128, v132
	v_cvt_pk_fp8_f32 v9, v136, v140
	v_cvt_pk_fp8_f32 v10, v144, v148
	v_cvt_pk_fp8_f32 v11, v152, v156
	v_and_b32_e32 v8, 0xffff, v8
	v_and_b32_e32 v10, 0xffff, v10
	v_lshl_or_b32 v184, v9, 16, v8
	v_lshl_or_b32 v185, v11, 16, v10
	global_store_dwordx2 v170, v[184:185], s[78:79]
	v_cvt_pk_fp8_f32 v8, v129, v133
	v_cvt_pk_fp8_f32 v9, v137, v141
	v_cvt_pk_fp8_f32 v10, v145, v149
	v_cvt_pk_fp8_f32 v11, v153, v157
	v_and_b32_e32 v8, 0xffff, v8
	v_and_b32_e32 v10, 0xffff, v10
	v_lshl_or_b32 v186, v9, 16, v8
	v_lshl_or_b32 v187, v11, 16, v10
	global_store_dwordx2 v171, v[186:187], s[78:79]
	v_cvt_pk_fp8_f32 v8, v130, v134
	v_cvt_pk_fp8_f32 v9, v138, v142
	v_cvt_pk_fp8_f32 v10, v146, v150
	v_cvt_pk_fp8_f32 v11, v154, v158
	v_and_b32_e32 v8, 0xffff, v8
	v_and_b32_e32 v10, 0xffff, v10
	v_lshl_or_b32 v188, v9, 16, v8
	v_lshl_or_b32 v189, v11, 16, v10
	global_store_dwordx2 v172, v[188:189], s[78:79]
	v_cvt_pk_fp8_f32 v8, v131, v135
	v_cvt_pk_fp8_f32 v9, v139, v143
	v_cvt_pk_fp8_f32 v10, v147, v151
	v_cvt_pk_fp8_f32 v11, v155, v159
	v_and_b32_e32 v8, 0xffff, v8
	v_and_b32_e32 v10, 0xffff, v10
	v_lshl_or_b32 v190, v9, 16, v8
	v_lshl_or_b32 v191, v11, 16, v10
	global_store_dwordx2 v173, v[190:191], s[78:79]
	s_branch .Lp0c_end

; __device__ __forceinline__ void own_barrier(unsigned* cnt, unsigned G) {
;     asm volatile("s_waitcnt vmcnt(0) lgkmcnt(0)" ::: "memory");
;     __syncthreads();
;     if (threadIdx.x == 0) {
;         __builtin_amdgcn_fence(__ATOMIC_RELEASE, "agent"); asm volatile("s_waitcnt vmcnt(0)" ::: "memory");
;         unsigned target;
;         if ((G & 7u) == 0u) { target = 8u;
;             const unsigned old = __hip_atomic_fetch_add(cnt + 64 * (1 + (blockIdx.x & 7)), 1u, __ATOMIC_RELAXED, __HIP_MEMORY_SCOPE_AGENT);
;             if (old + 1u == (G >> 3)) __hip_atomic_fetch_add(cnt, 1u, __ATOMIC_RELAXED, __HIP_MEMORY_SCOPE_AGENT); }
;         else { target = G; __hip_atomic_fetch_add(cnt, 1u, __ATOMIC_RELAXED, __HIP_MEMORY_SCOPE_AGENT); }
;         unsigned spins = 0;
;         while (__hip_atomic_load(cnt, __ATOMIC_RELAXED, __HIP_MEMORY_SCOPE_AGENT) < target && ++spins < (1u << 22)) __builtin_amdgcn_s_sleep(1);
;         __builtin_amdgcn_fence(__ATOMIC_ACQUIRE, "agent"); asm volatile("s_waitcnt vmcnt(0)" ::: "memory");
;     }
;     __syncthreads();
.LBB0_279:
	s_waitcnt vmcnt(0) lgkmcnt(0)
	v_cmp_eq_u32_e64 s[0:1], 0, v160
	v_cmp_ne_u32_e32 vcc, 0, v160
	s_waitcnt vmcnt(0)
	v_writelane_b32 v242, s0, 4
	s_barrier
	s_nop 0
	v_writelane_b32 v242, s1, 5
	s_and_saveexec_b64 s[0:1], vcc
	s_xor_b64 s[0:1], exec, s[0:1]
	s_and_b32 s4, s92, 7
	s_or_saveexec_b64 s[0:1], s[0:1]
	v_mov_b32_e32 v0, s4
	s_xor_b64 exec, exec, s[0:1]
	s_cbranch_execz .LBB0_301
	s_cmp_lg_u32 s92, 0x100
	s_cbranch_scc1 .Lseam1_orig
	buffer_wbl2 sc1
	s_waitcnt vmcnt(0)
	v_mov_b32_e32 v1, 0x8e01000
	v_mov_b32_e32 v2, 1
	global_atomic_add v2, v1, v2, s[90:91] sc0
	s_lshl_b32 s100, s2, 12
	s_add_u32 s100, s100, 0x8e10000
	v_mov_b32_e32 v1, s100
	s_waitcnt vmcnt(0)
	v_readfirstlane_b32 s100, v2
	s_cmp_eq_u32 s100, 0xff
	s_cbranch_scc0 .Lseam1_wait
	s_mov_b64 exec, -1
	v_mbcnt_lo_u32_b32 v243, -1, 0
	v_mbcnt_hi_u32_b32 v243, -1, v243
	v_lshlrev_b32_e32 v243, 12, v243
	v_add_u32_e32 v243, 0x8e10000, v243
	v_mov_b32_e32 v244, 1
	global_store_dword v243, v244, s[90:91] sc1
	v_add_u32_e32 v243, 0x40000, v243
	global_store_dword v243, v244, s[90:91] sc1
	v_add_u32_e32 v243, 0x40000, v243
	global_store_dword v243, v244, s[90:91] sc1
	v_add_u32_e32 v243, 0x40000, v243
	global_store_dword v243, v244, s[90:91] sc1
	s_mov_b64 exec, 1
	s_branch .Lseam1_done
.Lseam1_wait:
	s_mov_b32 s100, 0x400000
.Lseam1_poll:
	global_load_dword v2, v1, s[90:91] sc1
	s_waitcnt vmcnt(0)
	v_cmp_eq_u32_e32 vcc, 1, v2
	s_cbranch_vccnz .Lseam1_done
	s_sleep 1
	s_add_i32 s100, s100, -1
	s_cmp_lg_u32 s100, 0
	s_cbranch_scc1 .Lseam1_poll
.Lseam1_done:
	buffer_inv sc1
	s_waitcnt vmcnt(0)
	s_and_b32 s12, s92, 7
	s_branch .Lseam1_join

; __device__ __forceinline__ void own_barrier(unsigned* cnt, unsigned G) {
;     asm volatile("s_waitcnt vmcnt(0) lgkmcnt(0)" ::: "memory");
;     __syncthreads();
;     if (threadIdx.x == 0) {
;         __builtin_amdgcn_fence(__ATOMIC_RELEASE, "agent"); asm volatile("s_waitcnt vmcnt(0)" ::: "memory");
;         unsigned target;
;         if ((G & 7u) == 0u) { target = 8u;
;             const unsigned old = __hip_atomic_fetch_add(cnt + 64 * (1 + (blockIdx.x & 7)), 1u, __ATOMIC_RELAXED, __HIP_MEMORY_SCOPE_AGENT);
;             if (old + 1u == (G >> 3)) __hip_atomic_fetch_add(cnt, 1u, __ATOMIC_RELAXED, __HIP_MEMORY_SCOPE_AGENT); }
;         else { target = G; __hip_atomic_fetch_add(cnt, 1u, __ATOMIC_RELAXED, __HIP_MEMORY_SCOPE_AGENT); }
;         unsigned spins = 0;
;         while (__hip_atomic_load(cnt, __ATOMIC_RELAXED, __HIP_MEMORY_SCOPE_AGENT) < target && ++spins < (1u << 22)) __builtin_amdgcn_s_sleep(1);
;         __builtin_amdgcn_fence(__ATOMIC_ACQUIRE, "agent"); asm volatile("s_waitcnt vmcnt(0)" ::: "memory");
;     }
;     __syncthreads();
.LBB0_340:
	s_waitcnt vmcnt(0) lgkmcnt(0)
	s_barrier
	s_mov_b64 s[4:5], exec
	v_readlane_b32 s8, v242, 4
	v_readlane_b32 s9, v242, 5
	s_and_b64 s[8:9], s[4:5], s[8:9]
	s_mov_b64 exec, s[8:9]
	s_cbranch_execz .LBB0_366
	s_cmp_lg_u32 s92, 0x100
	s_cbranch_scc1 .Lseam2_orig
	buffer_wbl2 sc1
	s_waitcnt vmcnt(0)
	v_mov_b32_e32 v1, 0x8e02000
	v_mov_b32_e32 v2, 1
	global_atomic_add v2, v1, v2, s[90:91] sc0
	s_lshl_b32 s100, s2, 12
	s_add_u32 s100, s100, 0x8e10000
	v_mov_b32_e32 v1, s100
	s_waitcnt vmcnt(0)
	v_readfirstlane_b32 s100, v2
	s_cmp_eq_u32 s100, 0xff
	s_cbranch_scc0 .Lseam2_wait
	s_mov_b64 exec, -1
	v_mbcnt_lo_u32_b32 v243, -1, 0
	v_mbcnt_hi_u32_b32 v243, -1, v243
	v_lshlrev_b32_e32 v243, 12, v243
	v_add_u32_e32 v243, 0x8e10000, v243
	v_mov_b32_e32 v244, 2
	global_store_dword v243, v244, s[90:91] sc1
	v_add_u32_e32 v243, 0x40000, v243
	global_store_dword v243, v244, s[90:91] sc1
	v_add_u32_e32 v243, 0x40000, v243
	global_store_dword v243, v244, s[90:91] sc1
	v_add_u32_e32 v243, 0x40000, v243
	global_store_dword v243, v244, s[90:91] sc1
	s_mov_b64 exec, 1
	s_branch .Lseam2_done

; __device__ __forceinline__ void own_barrier(unsigned* cnt, unsigned G) {
;     asm volatile("s_waitcnt vmcnt(0) lgkmcnt(0)" ::: "memory");
;     __syncthreads();
;     if (threadIdx.x == 0) {
;         __builtin_amdgcn_fence(__ATOMIC_RELEASE, "agent"); asm volatile("s_waitcnt vmcnt(0)" ::: "memory");
;         unsigned target;
;         if ((G & 7u) == 0u) { target = 8u;
;             const unsigned old = __hip_atomic_fetch_add(cnt + 64 * (1 + (blockIdx.x & 7)), 1u, __ATOMIC_RELAXED, __HIP_MEMORY_SCOPE_AGENT);
;             if (old + 1u == (G >> 3)) __hip_atomic_fetch_add(cnt, 1u, __ATOMIC_RELAXED, __HIP_MEMORY_SCOPE_AGENT); }
;         else { target = G; __hip_atomic_fetch_add(cnt, 1u, __ATOMIC_RELAXED, __HIP_MEMORY_SCOPE_AGENT); }
;         unsigned spins = 0;
;         while (__hip_atomic_load(cnt, __ATOMIC_RELAXED, __HIP_MEMORY_SCOPE_AGENT) < target && ++spins < (1u << 22)) __builtin_amdgcn_s_sleep(1);
;         __builtin_amdgcn_fence(__ATOMIC_ACQUIRE, "agent"); asm volatile("s_waitcnt vmcnt(0)" ::: "memory");
;     }
;     __syncthreads();
.Lseam2_poll:
	global_load_dword v2, v1, s[90:91] sc1
	s_waitcnt vmcnt(0)
	v_cmp_eq_u32_e32 vcc, 2, v2
	s_cbranch_vccnz .Lseam2_done
	s_sleep 1
	s_add_i32 s100, s100, -1
	s_cmp_lg_u32 s100, 0
	s_cbranch_scc1 .Lseam2_poll
.Lseam2_done:
	buffer_inv sc1
	s_waitcnt vmcnt(0)
	s_branch .Lseam2_join

; __device__ __forceinline__ void own_barrier(unsigned* cnt, unsigned G) {
;     asm volatile("s_waitcnt vmcnt(0) lgkmcnt(0)" ::: "memory");
;     __syncthreads();
;     if (threadIdx.x == 0) {
;         __builtin_amdgcn_fence(__ATOMIC_RELEASE, "agent"); asm volatile("s_waitcnt vmcnt(0)" ::: "memory");
;         unsigned target;
;         if ((G & 7u) == 0u) { target = 8u;
;             const unsigned old = __hip_atomic_fetch_add(cnt + 64 * (1 + (blockIdx.x & 7)), 1u, __ATOMIC_RELAXED, __HIP_MEMORY_SCOPE_AGENT);
;             if (old + 1u == (G >> 3)) __hip_atomic_fetch_add(cnt, 1u, __ATOMIC_RELAXED, __HIP_MEMORY_SCOPE_AGENT); }
;         else { target = G; __hip_atomic_fetch_add(cnt, 1u, __ATOMIC_RELAXED, __HIP_MEMORY_SCOPE_AGENT); }
;         unsigned spins = 0;
;         while (__hip_atomic_load(cnt, __ATOMIC_RELAXED, __HIP_MEMORY_SCOPE_AGENT) < target && ++spins < (1u << 22)) __builtin_amdgcn_s_sleep(1);
;         __builtin_amdgcn_fence(__ATOMIC_ACQUIRE, "agent"); asm volatile("s_waitcnt vmcnt(0)" ::: "memory");
;     }
;     __syncthreads();
.LBB0_371:
	s_waitcnt vmcnt(0) lgkmcnt(0)
	v_readlane_b32 s62, v242, 4
	v_readlane_b32 s63, v242, 5
	s_barrier
	s_and_saveexec_b64 s[0:1], s[62:63]
	s_cbranch_execz .LBB0_397
	s_cmp_lg_u32 s92, 0x100
	s_cbranch_scc1 .Lseam3_orig
	buffer_wbl2 sc1
	s_waitcnt vmcnt(0)
	v_mov_b32_e32 v1, 0x8e03000
	v_mov_b32_e32 v2, 1
	global_atomic_add v2, v1, v2, s[90:91] sc0
	s_lshl_b32 s100, s2, 12
	s_add_u32 s100, s100, 0x8e10000
	v_mov_b32_e32 v1, s100
	s_waitcnt vmcnt(0)
	v_readfirstlane_b32 s100, v2
	s_cmp_eq_u32 s100, 0xff
	s_cbranch_scc0 .Lseam3_wait
	s_mov_b64 exec, -1
	v_mbcnt_lo_u32_b32 v243, -1, 0
	v_mbcnt_hi_u32_b32 v243, -1, v243
	v_lshlrev_b32_e32 v243, 12, v243
	v_add_u32_e32 v243, 0x8e10000, v243
	v_mov_b32_e32 v244, 3
	global_store_dword v243, v244, s[90:91] sc1
	v_add_u32_e32 v243, 0x40000, v243
	global_store_dword v243, v244, s[90:91] sc1
	v_add_u32_e32 v243, 0x40000, v243
	global_store_dword v243, v244, s[90:91] sc1
	v_add_u32_e32 v243, 0x40000, v243
	global_store_dword v243, v244, s[90:91] sc1
	s_mov_b64 exec, 1
	s_branch .Lseam3_done

; __device__ __forceinline__ void own_barrier(unsigned* cnt, unsigned G) {
;     asm volatile("s_waitcnt vmcnt(0) lgkmcnt(0)" ::: "memory");
;     __syncthreads();
;     if (threadIdx.x == 0) {
;         __builtin_amdgcn_fence(__ATOMIC_RELEASE, "agent"); asm volatile("s_waitcnt vmcnt(0)" ::: "memory");
;         unsigned target;
;         if ((G & 7u) == 0u) { target = 8u;
;             const unsigned old = __hip_atomic_fetch_add(cnt + 64 * (1 + (blockIdx.x & 7)), 1u, __ATOMIC_RELAXED, __HIP_MEMORY_SCOPE_AGENT);
;             if (old + 1u == (G >> 3)) __hip_atomic_fetch_add(cnt, 1u, __ATOMIC_RELAXED, __HIP_MEMORY_SCOPE_AGENT); }
;         else { target = G; __hip_atomic_fetch_add(cnt, 1u, __ATOMIC_RELAXED, __HIP_MEMORY_SCOPE_AGENT); }
;         unsigned spins = 0;
;         while (__hip_atomic_load(cnt, __ATOMIC_RELAXED, __HIP_MEMORY_SCOPE_AGENT) < target && ++spins < (1u << 22)) __builtin_amdgcn_s_sleep(1);
;         __builtin_amdgcn_fence(__ATOMIC_ACQUIRE, "agent"); asm volatile("s_waitcnt vmcnt(0)" ::: "memory");
;     }
;     __syncthreads();
.Lseam3_poll:
	global_load_dword v2, v1, s[90:91] sc1
	s_waitcnt vmcnt(0)
	v_cmp_eq_u32_e32 vcc, 3, v2
	s_cbranch_vccnz .Lseam3_done
	s_sleep 1
	s_add_i32 s100, s100, -1
	s_cmp_lg_u32 s100, 0
	s_cbranch_scc1 .Lseam3_poll

; __device__ __forceinline__ void own_barrier(unsigned* cnt, unsigned G) {
;     asm volatile("s_waitcnt vmcnt(0) lgkmcnt(0)" ::: "memory");
;     __syncthreads();
;     if (threadIdx.x == 0) {
;         __builtin_amdgcn_fence(__ATOMIC_RELEASE, "agent"); asm volatile("s_waitcnt vmcnt(0)" ::: "memory");
;         unsigned target;
;         if ((G & 7u) == 0u) { target = 8u;
;             const unsigned old = __hip_atomic_fetch_add(cnt + 64 * (1 + (blockIdx.x & 7)), 1u, __ATOMIC_RELAXED, __HIP_MEMORY_SCOPE_AGENT);
;             if (old + 1u == (G >> 3)) __hip_atomic_fetch_add(cnt, 1u, __ATOMIC_RELAXED, __HIP_MEMORY_SCOPE_AGENT); }
;         else { target = G; __hip_atomic_fetch_add(cnt, 1u, __ATOMIC_RELAXED, __HIP_MEMORY_SCOPE_AGENT); }
;         unsigned spins = 0;
;         while (__hip_atomic_load(cnt, __ATOMIC_RELAXED, __HIP_MEMORY_SCOPE_AGENT) < target && ++spins < (1u << 22)) __builtin_amdgcn_s_sleep(1);
;         __builtin_amdgcn_fence(__ATOMIC_ACQUIRE, "agent"); asm volatile("s_waitcnt vmcnt(0)" ::: "memory");
;     }
;     __syncthreads();
.LBB0_431:
	s_waitcnt vmcnt(0) lgkmcnt(0)
	s_waitcnt vmcnt(0)
	s_barrier
	s_and_saveexec_b64 s[4:5], s[62:63]
	s_cbranch_execz .LBB0_457
	s_cmp_lg_u32 s92, 0x100
	s_cbranch_scc1 .Lseam4_orig
	buffer_wbl2 sc1
	s_waitcnt vmcnt(0)
	v_mov_b32_e32 v1, 0x8e04000
	v_mov_b32_e32 v2, 1
	global_atomic_add v2, v1, v2, s[90:91] sc0
	s_lshl_b32 s100, s2, 12
	s_add_u32 s100, s100, 0x8e10000
	v_mov_b32_e32 v1, s100
	s_waitcnt vmcnt(0)
	v_readfirstlane_b32 s100, v2
	s_cmp_eq_u32 s100, 0xff
	s_cbranch_scc0 .Lseam4_wait
	s_mov_b64 exec, -1
	v_mbcnt_lo_u32_b32 v243, -1, 0
	v_mbcnt_hi_u32_b32 v243, -1, v243
	v_lshlrev_b32_e32 v243, 12, v243
	v_add_u32_e32 v243, 0x8e10000, v243
	v_mov_b32_e32 v244, 4
	global_store_dword v243, v244, s[90:91] sc1
	v_add_u32_e32 v243, 0x40000, v243
	global_store_dword v243, v244, s[90:91] sc1
	v_add_u32_e32 v243, 0x40000, v243
	global_store_dword v243, v244, s[90:91] sc1
	v_add_u32_e32 v243, 0x40000, v243
	global_store_dword v243, v244, s[90:91] sc1
	s_mov_b64 exec, 1
	s_branch .Lseam4_done

; __device__ __forceinline__ void own_barrier(unsigned* cnt, unsigned G) {
;     asm volatile("s_waitcnt vmcnt(0) lgkmcnt(0)" ::: "memory");
;     __syncthreads();
;     if (threadIdx.x == 0) {
;         __builtin_amdgcn_fence(__ATOMIC_RELEASE, "agent"); asm volatile("s_waitcnt vmcnt(0)" ::: "memory");
;         unsigned target;
;         if ((G & 7u) == 0u) { target = 8u;
;             const unsigned old = __hip_atomic_fetch_add(cnt + 64 * (1 + (blockIdx.x & 7)), 1u, __ATOMIC_RELAXED, __HIP_MEMORY_SCOPE_AGENT);
;             if (old + 1u == (G >> 3)) __hip_atomic_fetch_add(cnt, 1u, __ATOMIC_RELAXED, __HIP_MEMORY_SCOPE_AGENT); }
;         else { target = G; __hip_atomic_fetch_add(cnt, 1u, __ATOMIC_RELAXED, __HIP_MEMORY_SCOPE_AGENT); }
;         unsigned spins = 0;
;         while (__hip_atomic_load(cnt, __ATOMIC_RELAXED, __HIP_MEMORY_SCOPE_AGENT) < target && ++spins < (1u << 22)) __builtin_amdgcn_s_sleep(1);
;         __builtin_amdgcn_fence(__ATOMIC_ACQUIRE, "agent"); asm volatile("s_waitcnt vmcnt(0)" ::: "memory");
;     }
;     __syncthreads();
.Lseam4_poll:
	global_load_dword v2, v1, s[90:91] sc1
	s_waitcnt vmcnt(0)
	v_cmp_eq_u32_e32 vcc, 4, v2
	s_cbranch_vccnz .Lseam4_done
	s_sleep 1
	s_add_i32 s100, s100, -1
	s_cmp_lg_u32 s100, 0
	s_cbranch_scc1 .Lseam4_poll

; __device__ __forceinline__ void own_barrier(unsigned* cnt, unsigned G) {
;     asm volatile("s_waitcnt vmcnt(0) lgkmcnt(0)" ::: "memory");
;     __syncthreads();
;     if (threadIdx.x == 0) {
;         __builtin_amdgcn_fence(__ATOMIC_RELEASE, "agent"); asm volatile("s_waitcnt vmcnt(0)" ::: "memory");
;         unsigned target;
;         if ((G & 7u) == 0u) { target = 8u;
;             const unsigned old = __hip_atomic_fetch_add(cnt + 64 * (1 + (blockIdx.x & 7)), 1u, __ATOMIC_RELAXED, __HIP_MEMORY_SCOPE_AGENT);
;             if (old + 1u == (G >> 3)) __hip_atomic_fetch_add(cnt, 1u, __ATOMIC_RELAXED, __HIP_MEMORY_SCOPE_AGENT); }
;         else { target = G; __hip_atomic_fetch_add(cnt, 1u, __ATOMIC_RELAXED, __HIP_MEMORY_SCOPE_AGENT); }
;         unsigned spins = 0;
;         while (__hip_atomic_load(cnt, __ATOMIC_RELAXED, __HIP_MEMORY_SCOPE_AGENT) < target && ++spins < (1u << 22)) __builtin_amdgcn_s_sleep(1);
;         __builtin_amdgcn_fence(__ATOMIC_ACQUIRE, "agent"); asm volatile("s_waitcnt vmcnt(0)" ::: "memory");
;     }
;     __syncthreads();
.LBB0_499:
	s_waitcnt vmcnt(0) lgkmcnt(0)
	s_waitcnt lgkmcnt(0)
	s_barrier
	s_and_saveexec_b64 s[4:5], s[62:63]
	s_cbranch_execz .LBB0_525
	s_cmp_lg_u32 s92, 0x100
	s_cbranch_scc1 .Lseam5_orig
	buffer_wbl2 sc1
	s_waitcnt vmcnt(0)
	v_mov_b32_e32 v1, 0x8e05000
	v_mov_b32_e32 v2, 1
	global_atomic_add v2, v1, v2, s[90:91] sc0
	s_lshl_b32 s100, s2, 12
	s_add_u32 s100, s100, 0x8e10000
	v_mov_b32_e32 v1, s100
	s_waitcnt vmcnt(0)
	v_readfirstlane_b32 s100, v2
	s_cmp_eq_u32 s100, 0xff
	s_cbranch_scc0 .Lseam5_wait
	s_mov_b64 exec, -1
	v_mbcnt_lo_u32_b32 v243, -1, 0
	v_mbcnt_hi_u32_b32 v243, -1, v243
	v_lshlrev_b32_e32 v243, 12, v243
	v_add_u32_e32 v243, 0x8e10000, v243
	v_mov_b32_e32 v244, 5
	global_store_dword v243, v244, s[90:91] sc1
	v_add_u32_e32 v243, 0x40000, v243
	global_store_dword v243, v244, s[90:91] sc1
	v_add_u32_e32 v243, 0x40000, v243
	global_store_dword v243, v244, s[90:91] sc1
	v_add_u32_e32 v243, 0x40000, v243
	global_store_dword v243, v244, s[90:91] sc1
	s_mov_b64 exec, 1
	s_branch .Lseam5_done

; __device__ __forceinline__ void own_barrier(unsigned* cnt, unsigned G) {
;     asm volatile("s_waitcnt vmcnt(0) lgkmcnt(0)" ::: "memory");
;     __syncthreads();
;     if (threadIdx.x == 0) {
;         __builtin_amdgcn_fence(__ATOMIC_RELEASE, "agent"); asm volatile("s_waitcnt vmcnt(0)" ::: "memory");
;         unsigned target;
;         if ((G & 7u) == 0u) { target = 8u;
;             const unsigned old = __hip_atomic_fetch_add(cnt + 64 * (1 + (blockIdx.x & 7)), 1u, __ATOMIC_RELAXED, __HIP_MEMORY_SCOPE_AGENT);
;             if (old + 1u == (G >> 3)) __hip_atomic_fetch_add(cnt, 1u, __ATOMIC_RELAXED, __HIP_MEMORY_SCOPE_AGENT); }
;         else { target = G; __hip_atomic_fetch_add(cnt, 1u, __ATOMIC_RELAXED, __HIP_MEMORY_SCOPE_AGENT); }
;         unsigned spins = 0;
;         while (__hip_atomic_load(cnt, __ATOMIC_RELAXED, __HIP_MEMORY_SCOPE_AGENT) < target && ++spins < (1u << 22)) __builtin_amdgcn_s_sleep(1);
;         __builtin_amdgcn_fence(__ATOMIC_ACQUIRE, "agent"); asm volatile("s_waitcnt vmcnt(0)" ::: "memory");
;     }
;     __syncthreads();
.Lseam5_poll:
	global_load_dword v2, v1, s[90:91] sc1
	s_waitcnt vmcnt(0)
	v_cmp_eq_u32_e32 vcc, 5, v2
	s_cbranch_vccnz .Lseam5_done
	s_sleep 1
	s_add_i32 s100, s100, -1
	s_cmp_lg_u32 s100, 0
	s_cbranch_scc1 .Lseam5_poll
